# MFMA order: accumulator pairs (k0,k1 back to back) visited n-major: four consecutive pairs share the B-operand fragment (weight columns), token-row fragment changes every pair
# speedup vs baseline: 1.0882x; 1.0061x over previous
; #define PG8_STAGE(bufoff, gbase, voff) do { _Pragma("unroll") for (int _i = 0; _i < 2; ++_i) \
;         __builtin_amdgcn_global_load_lds((const unsigned*)((const char*)(gbase) + (voff)[_i]), (PG8_LAS unsigned*)(lds + (bufoff) + ldsw + _i * 8192), 16, 0, 0); } while (0)
; #define PG8_LDA(dst, b, h) do { _Pragma("unroll") for (int m = 0; m < 4; ++m) _Pragma("unroll") for (int k = 0; k < 2; ++k) dst[m][k] = *(const PG8_LAS bf16x8*)(lds + PG8_SA(b, h) + aoff + m * 2048 + k * 1024); } while (0)
; #define PG8_LDB(dst, b, h) do { _Pragma("unroll") for (int n = 0; n < 2; ++n) _Pragma("unroll") for (int k = 0; k < 2; ++k) dst[n][k] = *(const PG8_LAS bf16x8*)(lds + PG8_SB(b, h) + boff + n * 2048 + k * 1024); } while (0)
; #define PG8_WAIT_L(n) asm volatile("s_waitcnt lgkmcnt(" #n ")" ::: "memory")
; #define PG8_WAIT_V_SEL(sel) asm volatile("s_cmp_eq_u32 %0, 0\n\ts_cbranch_scc1 .Lw8_%=\n\ts_waitcnt vmcnt(22)\n\ts_branch .Lwd_%=\n.Lw8_%=:\n\ts_waitcnt vmcnt(8)\n.Lwd_%=:" :: "s"(sel) : "memory", "scc")
; #define PG8_BAR __builtin_amdgcn_s_barrier()
; #define PG8_SCHED __builtin_amdgcn_sched_barrier(0)
;     ...
;         for (int t = 0; t < nt * KREP; t += 2) {
;             const bool last = (t == nt * KREP - 2);
;             const int t1w = KREP > 1 ? ((t + 1) & (nt - 1)) : t + 1, t2w = KREP > 1 ? ((t + 2) & (nt - 1)) : t + 2;
;             const char* a1 = cA + (size_t)t1w * kstep;
;             const char* a2 = last ? nA : cA + (size_t)t2w * kstep; const char* b2 = last ? nB : cB + (size_t)t2w * kstep;
;             const char* a3 = a2 + kstep; const char* b3 = b2 + kstep;
;             if (last && has_next) S.a_ready(nxt);
;             const int relax = __builtin_amdgcn_readfirstlane((MK_RELAXW && t == 0 && ui > 0) ? 1 : 0);
;             if constexpr (SP2) {
;             PG8_LDB(B0, 0, 0); PG8_LDB(B1, 0, 1); PG8_SCHED; PG8_LDA(At, 0, 0); PG8_STAGE(PG8_SA(1, 1), a1 + hstep, voffA);
;             PG8_WAIT_V_SEL(relax);
;             PG8_WAIT_L(0); PG8_BAR; PG8_MMA(0, 0, At, B0); PG8_MMA(0, 1, At, B1); PG8_BAR; PG8_SCHED;
;             PG8_LDA(At, 0, 1); PG8_STAGE(PG8_SB(0, 0), b2, voffB); PG8_STAGE(PG8_SB(0, 1), b2 + hstep, voffB); PG8_STAGE(PG8_SA(0, 0), a2, voffA);
;             PG8_WAIT_V_SEL(relax);
;             PG8_WAIT_L(0); PG8_BAR; PG8_MMA(1, 0, At, B0); PG8_MMA(1, 1, At, B1); PG8_BAR; PG8_SCHED;
.LBB0_234:
	s_add_u32 s0, s78, 0xfff80080
	s_addc_u32 s1, s79, -1
	s_add_i32 s40, 0, 0x10000
	s_cmp_eq_u32 s37, 28
	s_cselect_b32 s83, s19, s1
	s_cselect_b32 s82, s20, s0
	s_cselect_b32 s81, s24, s35
	s_cselect_b32 s80, s31, s33
	s_add_i32 s41, 0, 0x14000
	ds_read_b128 v[142:145], v168
	ds_read_b128 v[146:149], v168 offset:1024
	ds_read_b128 v[150:153], v168 offset:2048
	ds_read_b128 v[154:157], v168 offset:3072
	ds_read_b128 v[158:161], v168 offset:16384
	ds_read_b128 v[162:165], v168 offset:17408
	ds_read_b128 v[174:177], v168 offset:18432
	ds_read_b128 v[188:191], v168 offset:19456
	s_add_i32 m0, s75, 0xc000
	ds_read_b128 v[198:201], v196
	ds_read_b128 v[202:205], v196 offset:1024
	ds_read_b128 v[206:209], v196 offset:2048
	ds_read_b128 v[210:213], v196 offset:3072
	ds_read_b128 v[214:217], v196 offset:4096
	ds_read_b128 v[218:221], v196 offset:5120
	ds_read_b128 v[222:225], v196 offset:6144
	ds_read_b128 v[226:229], v196 offset:7168
	global_load_lds_dwordx4 v138, s[78:79]
	s_add_i32 m0, s75, 0xe000
	s_nop 0
	global_load_lds_dwordx4 v140, s[78:79]
	s_waitcnt vmcnt(8)
	s_waitcnt lgkmcnt(0)
	s_setprio 1
	s_barrier
	v_mfma_f32_16x16x32_bf16 v[126:129], v[142:145], v[198:201], v[126:129]
	v_mfma_f32_16x16x32_bf16 v[126:129], v[146:149], v[202:205], v[126:129]
	v_mfma_f32_16x16x32_bf16 v[122:125], v[142:145], v[206:209], v[122:125]
	v_mfma_f32_16x16x32_bf16 v[122:125], v[146:149], v[210:213], v[122:125]
	v_mfma_f32_16x16x32_bf16 v[118:121], v[142:145], v[214:217], v[118:121]
	v_mfma_f32_16x16x32_bf16 v[118:121], v[146:149], v[218:221], v[118:121]
	v_mfma_f32_16x16x32_bf16 v[114:117], v[142:145], v[222:225], v[114:117]
	v_mfma_f32_16x16x32_bf16 v[114:117], v[146:149], v[226:229], v[114:117]
	v_mfma_f32_16x16x32_bf16 v[110:113], v[150:153], v[198:201], v[110:113]
	v_mfma_f32_16x16x32_bf16 v[110:113], v[154:157], v[202:205], v[110:113]
	v_mfma_f32_16x16x32_bf16 v[106:109], v[150:153], v[206:209], v[106:109]
	v_mfma_f32_16x16x32_bf16 v[106:109], v[154:157], v[210:213], v[106:109]
	v_mfma_f32_16x16x32_bf16 v[102:105], v[150:153], v[214:217], v[102:105]
	v_mfma_f32_16x16x32_bf16 v[102:105], v[154:157], v[218:221], v[102:105]
	v_mfma_f32_16x16x32_bf16 v[98:101], v[150:153], v[222:225], v[98:101]
	v_mfma_f32_16x16x32_bf16 v[98:101], v[154:157], v[226:229], v[98:101]
	v_mfma_f32_16x16x32_bf16 v[82:85], v[158:161], v[198:201], v[82:85]
	v_mfma_f32_16x16x32_bf16 v[82:85], v[162:165], v[202:205], v[82:85]
	v_mfma_f32_16x16x32_bf16 v[70:73], v[158:161], v[206:209], v[70:73]
	v_mfma_f32_16x16x32_bf16 v[70:73], v[162:165], v[210:213], v[70:73]
	v_mfma_f32_16x16x32_bf16 v[66:69], v[158:161], v[214:217], v[66:69]
	v_mfma_f32_16x16x32_bf16 v[66:69], v[162:165], v[218:221], v[66:69]
	v_mfma_f32_16x16x32_bf16 v[58:61], v[158:161], v[222:225], v[58:61]
	v_mfma_f32_16x16x32_bf16 v[58:61], v[162:165], v[226:229], v[58:61]
	v_mfma_f32_16x16x32_bf16 v[30:33], v[174:177], v[198:201], v[30:33]
	v_mfma_f32_16x16x32_bf16 v[30:33], v[188:191], v[202:205], v[30:33]
	v_mfma_f32_16x16x32_bf16 v[26:29], v[174:177], v[206:209], v[26:29]
	v_mfma_f32_16x16x32_bf16 v[26:29], v[188:191], v[210:213], v[26:29]
	v_mfma_f32_16x16x32_bf16 v[22:25], v[174:177], v[214:217], v[22:25]
	v_mfma_f32_16x16x32_bf16 v[22:25], v[188:191], v[218:221], v[22:25]
	v_mfma_f32_16x16x32_bf16 v[18:21], v[174:177], v[222:225], v[18:21]
	v_mfma_f32_16x16x32_bf16 v[18:21], v[188:191], v[226:229], v[18:21]
	s_barrier
	s_setprio 0
	s_add_i32 s0, s40, s87
	s_mov_b32 m0, s0
	ds_read_b128 v[198:201], v196 offset:16384
	ds_read_b128 v[202:205], v196 offset:17408
	ds_read_b128 v[206:209], v196 offset:18432
	ds_read_b128 v[210:213], v196 offset:19456
	ds_read_b128 v[214:217], v196 offset:20480
	ds_read_b128 v[218:221], v196 offset:21504
	ds_read_b128 v[222:225], v196 offset:22528
	ds_read_b128 v[226:229], v196 offset:23552
	global_load_lds_dwordx4 v182, s[80:81]
	s_add_i32 m0, s0, 0x2000
	s_add_u32 s0, s80, 0x80000
	s_addc_u32 s1, s81, 0
	s_add_i32 s40, s41, s87
	global_load_lds_dwordx4 v134, s[80:81]
	s_mov_b32 m0, s40
	s_nop 0
	global_load_lds_dwordx4 v182, s[0:1]
	s_add_i32 m0, s40, 0x2000
	s_nop 0
	global_load_lds_dwordx4 v134, s[0:1]
	s_mov_b32 m0, s75
	s_nop 0
	global_load_lds_dwordx4 v130, s[82:83]
	s_mov_b32 m0, s88
	s_nop 0
	global_load_lds_dwordx4 v132, s[82:83]
	s_waitcnt vmcnt(8)
	s_waitcnt lgkmcnt(0)
	s_setprio 1
	s_barrier
	v_mfma_f32_16x16x32_bf16 v[94:97], v[142:145], v[198:201], v[94:97]
	v_mfma_f32_16x16x32_bf16 v[94:97], v[146:149], v[202:205], v[94:97]
	v_mfma_f32_16x16x32_bf16 v[90:93], v[142:145], v[206:209], v[90:93]
	v_mfma_f32_16x16x32_bf16 v[90:93], v[146:149], v[210:213], v[90:93]
	v_mfma_f32_16x16x32_bf16 v[86:89], v[142:145], v[214:217], v[86:89]
	v_mfma_f32_16x16x32_bf16 v[86:89], v[146:149], v[218:221], v[86:89]
	v_mfma_f32_16x16x32_bf16 v[78:81], v[142:145], v[222:225], v[78:81]
	v_mfma_f32_16x16x32_bf16 v[78:81], v[146:149], v[226:229], v[78:81]
	v_mfma_f32_16x16x32_bf16 v[74:77], v[150:153], v[198:201], v[74:77]
	v_mfma_f32_16x16x32_bf16 v[74:77], v[154:157], v[202:205], v[74:77]
	v_mfma_f32_16x16x32_bf16 v[62:65], v[150:153], v[206:209], v[62:65]
	v_mfma_f32_16x16x32_bf16 v[62:65], v[154:157], v[210:213], v[62:65]
	v_mfma_f32_16x16x32_bf16 v[54:57], v[150:153], v[214:217], v[54:57]
	v_mfma_f32_16x16x32_bf16 v[54:57], v[154:157], v[218:221], v[54:57]
	v_mfma_f32_16x16x32_bf16 v[50:53], v[150:153], v[222:225], v[50:53]
	v_mfma_f32_16x16x32_bf16 v[50:53], v[154:157], v[226:229], v[50:53]
	v_mfma_f32_16x16x32_bf16 v[46:49], v[158:161], v[198:201], v[46:49]
	v_mfma_f32_16x16x32_bf16 v[46:49], v[162:165], v[202:205], v[46:49]
	v_mfma_f32_16x16x32_bf16 v[42:45], v[158:161], v[206:209], v[42:45]
	v_mfma_f32_16x16x32_bf16 v[42:45], v[162:165], v[210:213], v[42:45]
	v_mfma_f32_16x16x32_bf16 v[38:41], v[158:161], v[214:217], v[38:41]
	v_mfma_f32_16x16x32_bf16 v[38:41], v[162:165], v[218:221], v[38:41]
	v_mfma_f32_16x16x32_bf16 v[34:37], v[158:161], v[222:225], v[34:37]
	v_mfma_f32_16x16x32_bf16 v[34:37], v[162:165], v[226:229], v[34:37]
	v_mfma_f32_16x16x32_bf16 v[14:17], v[174:177], v[198:201], v[14:17]
	v_mfma_f32_16x16x32_bf16 v[14:17], v[188:191], v[202:205], v[14:17]
	v_mfma_f32_16x16x32_bf16 v[10:13], v[174:177], v[206:209], v[10:13]
	v_mfma_f32_16x16x32_bf16 v[10:13], v[188:191], v[210:213], v[10:13]
	v_mfma_f32_16x16x32_bf16 v[6:9], v[174:177], v[214:217], v[6:9]
	v_mfma_f32_16x16x32_bf16 v[6:9], v[188:191], v[218:221], v[6:9]
	v_mfma_f32_16x16x32_bf16 v[2:5], v[174:177], v[222:225], v[2:5]
	v_mfma_f32_16x16x32_bf16 v[2:5], v[188:191], v[226:229], v[2:5]
	s_barrier
; #define PG8_STAGE(bufoff, gbase, voff) do { _Pragma("unroll") for (int _i = 0; _i < 2; ++_i) \
;         __builtin_amdgcn_global_load_lds((const unsigned*)((const char*)(gbase) + (voff)[_i]), (PG8_LAS unsigned*)(lds + (bufoff) + ldsw + _i * 8192), 16, 0, 0); } while (0)
; #define PG8_LDA(dst, b, h) do { _Pragma("unroll") for (int m = 0; m < 4; ++m) _Pragma("unroll") for (int k = 0; k < 2; ++k) dst[m][k] = *(const PG8_LAS bf16x8*)(lds + PG8_SA(b, h) + aoff + m * 2048 + k * 1024); } while (0)
; #define PG8_LDB(dst, b, h) do { _Pragma("unroll") for (int n = 0; n < 2; ++n) _Pragma("unroll") for (int k = 0; k < 2; ++k) dst[n][k] = *(const PG8_LAS bf16x8*)(lds + PG8_SB(b, h) + boff + n * 2048 + k * 1024); } while (0)
; #define PG8_WAIT_V(n) asm volatile("s_waitcnt vmcnt(" #n ")" ::: "memory")
; #define PG8_WAIT_L(n) asm volatile("s_waitcnt lgkmcnt(" #n ")" ::: "memory")
; #define PG8_WAIT_V_SEL(sel) asm volatile("s_cmp_eq_u32 %0, 0\n\ts_cbranch_scc1 .Lw8_%=\n\ts_waitcnt vmcnt(22)\n\ts_branch .Lwd_%=\n.Lw8_%=:\n\ts_waitcnt vmcnt(8)\n.Lwd_%=:" :: "s"(sel) : "memory", "scc")
; #define PG8_BAR __builtin_amdgcn_s_barrier()
; #define PG8_SCHED __builtin_amdgcn_sched_barrier(0)
;     ...
;             PG8_LDB(B0, 0, 0); PG8_LDB(B1, 0, 1); PG8_SCHED; PG8_LDA(At, 0, 0); PG8_STAGE(PG8_SA(1, 1), a1 + hstep, voffA);
;             PG8_WAIT_V_SEL(relax);
;             PG8_WAIT_L(0); PG8_BAR; PG8_MMA(0, 0, At, B0); PG8_MMA(0, 1, At, B1); PG8_BAR; PG8_SCHED;
;             PG8_LDA(At, 0, 1); PG8_STAGE(PG8_SB(0, 0), b2, voffB); PG8_STAGE(PG8_SB(0, 1), b2 + hstep, voffB); PG8_STAGE(PG8_SA(0, 0), a2, voffA);
;             PG8_WAIT_V_SEL(relax);
;             PG8_WAIT_L(0); PG8_BAR; PG8_MMA(1, 0, At, B0); PG8_MMA(1, 1, At, B1); PG8_BAR; PG8_SCHED;
;             PG8_LDB(B0, 1, 0); PG8_LDB(B1, 1, 1); PG8_SCHED; PG8_LDA(At, 1, 0); PG8_STAGE(PG8_SA(0, 1), a2 + hstep, voffA);
;             PG8_WAIT_V(8); PG8_WAIT_L(0); PG8_BAR; PG8_MMA(0, 0, At, B0); PG8_MMA(0, 1, At, B1); PG8_BAR; PG8_SCHED;
;             PG8_LDA(At, 1, 1); PG8_STAGE(PG8_SB(1, 0), b3, voffB); PG8_STAGE(PG8_SB(1, 1), b3 + hstep, voffB); PG8_STAGE(PG8_SA(1, 0), a3, voffA);
;             PG8_WAIT_V(8); PG8_WAIT_L(0); PG8_BAR; PG8_MMA(1, 0, At, B0); PG8_MMA(1, 1, At, B1); PG8_BAR; PG8_SCHED;
	s_setprio 0
	s_add_i32 s40, 0, 0x18000
	s_add_i32 s41, 0, 0x1c000
	ds_read_b128 v[142:145], v168 offset:32768
	ds_read_b128 v[146:149], v168 offset:33792
	ds_read_b128 v[150:153], v168 offset:34816
	ds_read_b128 v[154:157], v168 offset:35840
	ds_read_b128 v[158:161], v168 offset:49152
	ds_read_b128 v[162:165], v168 offset:50176
	ds_read_b128 v[174:177], v168 offset:51200
	ds_read_b128 v[188:191], v168 offset:52224
	s_add_u32 s0, s82, 0x80000
	s_addc_u32 s1, s83, 0
	s_mov_b32 m0, s89
	ds_read_b128 v[198:201], v196 offset:32768
	ds_read_b128 v[202:205], v196 offset:33792
	ds_read_b128 v[206:209], v196 offset:34816
	ds_read_b128 v[210:213], v196 offset:35840
	ds_read_b128 v[214:217], v196 offset:36864
	ds_read_b128 v[218:221], v196 offset:37888
	ds_read_b128 v[222:225], v196 offset:38912
	ds_read_b128 v[226:229], v196 offset:39936
	global_load_lds_dwordx4 v130, s[0:1]
	s_mov_b32 m0, s90
	s_nop 0
	global_load_lds_dwordx4 v132, s[0:1]
	s_waitcnt vmcnt(8)
	s_waitcnt lgkmcnt(0)
	s_setprio 1
	s_barrier
	v_mfma_f32_16x16x32_bf16 v[126:129], v[142:145], v[198:201], v[126:129]
	v_mfma_f32_16x16x32_bf16 v[126:129], v[146:149], v[202:205], v[126:129]
	v_mfma_f32_16x16x32_bf16 v[122:125], v[142:145], v[206:209], v[122:125]
	v_mfma_f32_16x16x32_bf16 v[122:125], v[146:149], v[210:213], v[122:125]
	v_mfma_f32_16x16x32_bf16 v[118:121], v[142:145], v[214:217], v[118:121]
	v_mfma_f32_16x16x32_bf16 v[118:121], v[146:149], v[218:221], v[118:121]
	v_mfma_f32_16x16x32_bf16 v[114:117], v[142:145], v[222:225], v[114:117]
	v_mfma_f32_16x16x32_bf16 v[114:117], v[146:149], v[226:229], v[114:117]
	v_mfma_f32_16x16x32_bf16 v[110:113], v[150:153], v[198:201], v[110:113]
	v_mfma_f32_16x16x32_bf16 v[110:113], v[154:157], v[202:205], v[110:113]
	v_mfma_f32_16x16x32_bf16 v[106:109], v[150:153], v[206:209], v[106:109]
	v_mfma_f32_16x16x32_bf16 v[106:109], v[154:157], v[210:213], v[106:109]
	v_mfma_f32_16x16x32_bf16 v[102:105], v[150:153], v[214:217], v[102:105]
	v_mfma_f32_16x16x32_bf16 v[102:105], v[154:157], v[218:221], v[102:105]
	v_mfma_f32_16x16x32_bf16 v[98:101], v[150:153], v[222:225], v[98:101]
	v_mfma_f32_16x16x32_bf16 v[98:101], v[154:157], v[226:229], v[98:101]
	v_mfma_f32_16x16x32_bf16 v[82:85], v[158:161], v[198:201], v[82:85]
	v_mfma_f32_16x16x32_bf16 v[82:85], v[162:165], v[202:205], v[82:85]
	v_mfma_f32_16x16x32_bf16 v[70:73], v[158:161], v[206:209], v[70:73]
	v_mfma_f32_16x16x32_bf16 v[70:73], v[162:165], v[210:213], v[70:73]
	v_mfma_f32_16x16x32_bf16 v[66:69], v[158:161], v[214:217], v[66:69]
	v_mfma_f32_16x16x32_bf16 v[66:69], v[162:165], v[218:221], v[66:69]
	v_mfma_f32_16x16x32_bf16 v[58:61], v[158:161], v[222:225], v[58:61]
	v_mfma_f32_16x16x32_bf16 v[58:61], v[162:165], v[226:229], v[58:61]
	v_mfma_f32_16x16x32_bf16 v[30:33], v[174:177], v[198:201], v[30:33]
	v_mfma_f32_16x16x32_bf16 v[30:33], v[188:191], v[202:205], v[30:33]
	v_mfma_f32_16x16x32_bf16 v[26:29], v[174:177], v[206:209], v[26:29]
	v_mfma_f32_16x16x32_bf16 v[26:29], v[188:191], v[210:213], v[26:29]
	v_mfma_f32_16x16x32_bf16 v[22:25], v[174:177], v[214:217], v[22:25]
	v_mfma_f32_16x16x32_bf16 v[22:25], v[188:191], v[218:221], v[22:25]
	v_mfma_f32_16x16x32_bf16 v[18:21], v[174:177], v[222:225], v[18:21]
	v_mfma_f32_16x16x32_bf16 v[18:21], v[188:191], v[226:229], v[18:21]
	s_barrier
	s_setprio 0
	s_add_i32 s0, s40, s87
	s_mov_b32 m0, s0
	ds_read_b128 v[198:201], v196 offset:49152
	ds_read_b128 v[202:205], v196 offset:50176
	ds_read_b128 v[206:209], v196 offset:51200
	ds_read_b128 v[210:213], v196 offset:52224
	ds_read_b128 v[214:217], v196 offset:53248
	ds_read_b128 v[218:221], v196 offset:54272
	ds_read_b128 v[222:225], v196 offset:55296
	ds_read_b128 v[226:229], v196 offset:56320
	s_add_u32 s100, s80, 0x80
	s_addc_u32 s101, s81, 0
	global_load_lds_dwordx4 v182, s[100:101]
	s_add_i32 m0, s0, 0x2000
	s_add_u32 s0, s80, 0x80080
	s_addc_u32 s1, s81, 0
	s_add_i32 s40, s41, s87
	global_load_lds_dwordx4 v134, s[100:101]
	s_mov_b32 m0, s40
	s_nop 0
	global_load_lds_dwordx4 v182, s[0:1]
	s_add_i32 m0, s40, 0x2000
	s_nop 0
	global_load_lds_dwordx4 v134, s[0:1]
	s_mov_b32 m0, s94
	s_nop 0
	s_add_u32 s100, s82, 0x80
	s_addc_u32 s101, s83, 0
	global_load_lds_dwordx4 v130, s[100:101]
	s_mov_b32 m0, s95
	s_nop 0
	global_load_lds_dwordx4 v132, s[100:101]
	s_waitcnt vmcnt(8)
	s_waitcnt lgkmcnt(0)
	s_setprio 1
	s_barrier
	v_mfma_f32_16x16x32_bf16 v[94:97], v[142:145], v[198:201], v[94:97]
	v_mfma_f32_16x16x32_bf16 v[94:97], v[146:149], v[202:205], v[94:97]
	v_mfma_f32_16x16x32_bf16 v[90:93], v[142:145], v[206:209], v[90:93]
	v_mfma_f32_16x16x32_bf16 v[90:93], v[146:149], v[210:213], v[90:93]
	v_mfma_f32_16x16x32_bf16 v[86:89], v[142:145], v[214:217], v[86:89]
	v_mfma_f32_16x16x32_bf16 v[86:89], v[146:149], v[218:221], v[86:89]
	v_mfma_f32_16x16x32_bf16 v[78:81], v[142:145], v[222:225], v[78:81]
	v_mfma_f32_16x16x32_bf16 v[78:81], v[146:149], v[226:229], v[78:81]
	v_mfma_f32_16x16x32_bf16 v[74:77], v[150:153], v[198:201], v[74:77]
	v_mfma_f32_16x16x32_bf16 v[74:77], v[154:157], v[202:205], v[74:77]
	v_mfma_f32_16x16x32_bf16 v[62:65], v[150:153], v[206:209], v[62:65]
	v_mfma_f32_16x16x32_bf16 v[62:65], v[154:157], v[210:213], v[62:65]
	v_mfma_f32_16x16x32_bf16 v[54:57], v[150:153], v[214:217], v[54:57]
	v_mfma_f32_16x16x32_bf16 v[54:57], v[154:157], v[218:221], v[54:57]
	v_mfma_f32_16x16x32_bf16 v[50:53], v[150:153], v[222:225], v[50:53]
	v_mfma_f32_16x16x32_bf16 v[50:53], v[154:157], v[226:229], v[50:53]
	v_mfma_f32_16x16x32_bf16 v[46:49], v[158:161], v[198:201], v[46:49]
	v_mfma_f32_16x16x32_bf16 v[46:49], v[162:165], v[202:205], v[46:49]
	v_mfma_f32_16x16x32_bf16 v[42:45], v[158:161], v[206:209], v[42:45]
	v_mfma_f32_16x16x32_bf16 v[42:45], v[162:165], v[210:213], v[42:45]
	v_mfma_f32_16x16x32_bf16 v[38:41], v[158:161], v[214:217], v[38:41]
	v_mfma_f32_16x16x32_bf16 v[38:41], v[162:165], v[218:221], v[38:41]
	v_mfma_f32_16x16x32_bf16 v[34:37], v[158:161], v[222:225], v[34:37]
	v_mfma_f32_16x16x32_bf16 v[34:37], v[162:165], v[226:229], v[34:37]
	v_mfma_f32_16x16x32_bf16 v[14:17], v[174:177], v[198:201], v[14:17]
	v_mfma_f32_16x16x32_bf16 v[14:17], v[188:191], v[202:205], v[14:17]
	v_mfma_f32_16x16x32_bf16 v[10:13], v[174:177], v[206:209], v[10:13]
	v_mfma_f32_16x16x32_bf16 v[10:13], v[188:191], v[210:213], v[10:13]
	v_mfma_f32_16x16x32_bf16 v[6:9], v[174:177], v[214:217], v[6:9]
	v_mfma_f32_16x16x32_bf16 v[6:9], v[188:191], v[218:221], v[6:9]
	v_mfma_f32_16x16x32_bf16 v[2:5], v[174:177], v[222:225], v[2:5]
	v_mfma_f32_16x16x32_bf16 v[2:5], v[188:191], v[226:229], v[2:5]
	s_barrier
	s_setprio 0
	s_add_i32 s37, s37, 2
	s_add_u32 s78, s78, 0x100
	s_addc_u32 s79, s79, 0
	s_add_u32 s33, s33, 0x100
	s_addc_u32 s35, s35, 0
	s_cmp_gt_u32 s37, 29
	s_cbranch_scc0 .LBB0_234
	s_and_b64 vcc, exec, s[64:65]
	s_cbranch_vccz .LBB0_237
	s_barrier

; #define PG8_STAGE(bufoff, gbase, voff) do { _Pragma("unroll") for (int _i = 0; _i < 2; ++_i) \
;         __builtin_amdgcn_global_load_lds((const unsigned*)((const char*)(gbase) + (voff)[_i]), (PG8_LAS unsigned*)(lds + (bufoff) + ldsw + _i * 8192), 16, 0, 0); } while (0)
; #define PG8_LDA(dst, b, h) do { _Pragma("unroll") for (int m = 0; m < 4; ++m) _Pragma("unroll") for (int k = 0; k < 2; ++k) dst[m][k] = *(const PG8_LAS bf16x8*)(lds + PG8_SA(b, h) + aoff + m * 2048 + k * 1024); } while (0)
; #define PG8_LDB(dst, b, h) do { _Pragma("unroll") for (int n = 0; n < 2; ++n) _Pragma("unroll") for (int k = 0; k < 2; ++k) dst[n][k] = *(const PG8_LAS bf16x8*)(lds + PG8_SB(b, h) + boff + n * 2048 + k * 1024); } while (0)
; #define PG8_WAIT_L(n) asm volatile("s_waitcnt lgkmcnt(" #n ")" ::: "memory")
; #define PG8_WAIT_V_SEL(sel) asm volatile("s_cmp_eq_u32 %0, 0\n\ts_cbranch_scc1 .Lw8_%=\n\ts_waitcnt vmcnt(22)\n\ts_branch .Lwd_%=\n.Lw8_%=:\n\ts_waitcnt vmcnt(8)\n.Lwd_%=:" :: "s"(sel) : "memory", "scc")
; #define PG8_BAR __builtin_amdgcn_s_barrier()
; #define PG8_SCHED __builtin_amdgcn_sched_barrier(0)
;     ...
;         for (int t = 0; t < nt * KREP; t += 2) {
;             const bool last = (t == nt * KREP - 2);
;             const int t1w = KREP > 1 ? ((t + 1) & (nt - 1)) : t + 1, t2w = KREP > 1 ? ((t + 2) & (nt - 1)) : t + 2;
;             const char* a1 = cA + (size_t)t1w * kstep;
;             const char* a2 = last ? nA : cA + (size_t)t2w * kstep; const char* b2 = last ? nB : cB + (size_t)t2w * kstep;
;             const char* a3 = a2 + kstep; const char* b3 = b2 + kstep;
;             if (last && has_next) S.a_ready(nxt);
;             const int relax = __builtin_amdgcn_readfirstlane((MK_RELAXW && t == 0 && ui > 0) ? 1 : 0);
;             if constexpr (SP2) {
;             PG8_LDB(B0, 0, 0); PG8_LDB(B1, 0, 1); PG8_SCHED; PG8_LDA(At, 0, 0); PG8_STAGE(PG8_SA(1, 1), a1 + hstep, voffA);
;             PG8_WAIT_V_SEL(relax);
;             PG8_WAIT_L(0); PG8_BAR; PG8_MMA(0, 0, At, B0); PG8_MMA(0, 1, At, B1); PG8_BAR; PG8_SCHED;
;             PG8_LDA(At, 0, 1); PG8_STAGE(PG8_SB(0, 0), b2, voffB); PG8_STAGE(PG8_SB(0, 1), b2 + hstep, voffB); PG8_STAGE(PG8_SA(0, 0), a2, voffA);
;             PG8_WAIT_V_SEL(relax);
;             PG8_WAIT_L(0); PG8_BAR; PG8_MMA(1, 0, At, B0); PG8_MMA(1, 1, At, B1); PG8_BAR; PG8_SCHED;
.LBB0_541:
	s_add_u32 s0, s82, 0xfff80080
	s_addc_u32 s1, s83, -1
	s_add_i32 s79, 0, 0x10000
	s_cmp_eq_u32 s73, 28
	s_cselect_b32 s87, s40, s1
	s_cselect_b32 s86, s41, s0
	s_cselect_b32 s85, s57, s71
	s_cselect_b32 s84, s58, s59
	s_add_i32 s81, 0, 0x14000
	ds_read_b128 v[90:93], v210
	ds_read_b128 v[94:97], v210 offset:1024
	ds_read_b128 v[98:101], v210 offset:2048
	ds_read_b128 v[102:105], v210 offset:3072
	ds_read_b128 v[146:149], v210 offset:16384
	ds_read_b128 v[150:153], v210 offset:17408
	ds_read_b128 v[154:157], v210 offset:18432
	ds_read_b128 v[158:161], v210 offset:19456
	s_add_i32 m0, s44, 0xc000
	ds_read_b128 v[162:165], v230
	ds_read_b128 v[166:169], v230 offset:1024
	ds_read_b128 v[184:187], v230 offset:2048
	ds_read_b128 v[190:193], v230 offset:3072
	ds_read_b128 v[194:197], v230 offset:4096
	ds_read_b128 v[198:201], v230 offset:5120
	ds_read_b128 v[202:205], v230 offset:6144
	ds_read_b128 v[206:209], v230 offset:7168
	global_load_lds_dwordx4 v180, s[82:83]
	s_add_i32 m0, s44, 0xe000
	s_nop 0
	global_load_lds_dwordx4 v188, s[82:83]
	s_waitcnt vmcnt(8)
	s_waitcnt lgkmcnt(0)
	s_setprio 1
	s_barrier
	v_mfma_f32_16x16x32_bf16 v[142:145], v[90:93], v[162:165], v[142:145]
	v_mfma_f32_16x16x32_bf16 v[142:145], v[94:97], v[166:169], v[142:145]
	v_mfma_f32_16x16x32_bf16 v[126:129], v[90:93], v[184:187], v[126:129]
	v_mfma_f32_16x16x32_bf16 v[126:129], v[94:97], v[190:193], v[126:129]
	v_mfma_f32_16x16x32_bf16 v[110:113], v[90:93], v[194:197], v[110:113]
	v_mfma_f32_16x16x32_bf16 v[110:113], v[94:97], v[198:201], v[110:113]
	v_mfma_f32_16x16x32_bf16 v[78:81], v[90:93], v[202:205], v[78:81]
	v_mfma_f32_16x16x32_bf16 v[78:81], v[94:97], v[206:209], v[78:81]
	v_mfma_f32_16x16x32_bf16 v[138:141], v[98:101], v[162:165], v[138:141]
	v_mfma_f32_16x16x32_bf16 v[138:141], v[102:105], v[166:169], v[138:141]
	v_mfma_f32_16x16x32_bf16 v[122:125], v[98:101], v[184:187], v[122:125]
	v_mfma_f32_16x16x32_bf16 v[122:125], v[102:105], v[190:193], v[122:125]
	v_mfma_f32_16x16x32_bf16 v[106:109], v[98:101], v[194:197], v[106:109]
	v_mfma_f32_16x16x32_bf16 v[106:109], v[102:105], v[198:201], v[106:109]
	v_mfma_f32_16x16x32_bf16 v[74:77], v[98:101], v[202:205], v[74:77]
	v_mfma_f32_16x16x32_bf16 v[74:77], v[102:105], v[206:209], v[74:77]
	v_mfma_f32_16x16x32_bf16 v[134:137], v[146:149], v[162:165], v[134:137]
	v_mfma_f32_16x16x32_bf16 v[134:137], v[150:153], v[166:169], v[134:137]
	v_mfma_f32_16x16x32_bf16 v[118:121], v[146:149], v[184:187], v[118:121]
	v_mfma_f32_16x16x32_bf16 v[118:121], v[150:153], v[190:193], v[118:121]
	v_mfma_f32_16x16x32_bf16 v[86:89], v[146:149], v[194:197], v[86:89]
	v_mfma_f32_16x16x32_bf16 v[86:89], v[150:153], v[198:201], v[86:89]
	v_mfma_f32_16x16x32_bf16 v[70:73], v[146:149], v[202:205], v[70:73]
	v_mfma_f32_16x16x32_bf16 v[70:73], v[150:153], v[206:209], v[70:73]
	v_mfma_f32_16x16x32_bf16 v[130:133], v[154:157], v[162:165], v[130:133]
	v_mfma_f32_16x16x32_bf16 v[130:133], v[158:161], v[166:169], v[130:133]
	v_mfma_f32_16x16x32_bf16 v[114:117], v[154:157], v[184:187], v[114:117]
	v_mfma_f32_16x16x32_bf16 v[114:117], v[158:161], v[190:193], v[114:117]
	v_mfma_f32_16x16x32_bf16 v[82:85], v[154:157], v[194:197], v[82:85]
	v_mfma_f32_16x16x32_bf16 v[82:85], v[158:161], v[198:201], v[82:85]
	v_mfma_f32_16x16x32_bf16 v[66:69], v[154:157], v[202:205], v[66:69]
	v_mfma_f32_16x16x32_bf16 v[66:69], v[158:161], v[206:209], v[66:69]
	s_barrier
	s_setprio 0
	s_add_i32 s0, s79, s30
	s_mov_b32 m0, s0
	ds_read_b128 v[162:165], v230 offset:16384
	ds_read_b128 v[166:169], v230 offset:17408
	ds_read_b128 v[184:187], v230 offset:18432
	ds_read_b128 v[190:193], v230 offset:19456
	ds_read_b128 v[194:197], v230 offset:20480
	ds_read_b128 v[198:201], v230 offset:21504
	ds_read_b128 v[202:205], v230 offset:22528
	ds_read_b128 v[206:209], v230 offset:23552
	global_load_lds_dwordx4 v182, s[84:85]
	s_add_i32 m0, s0, 0x2000
	s_add_u32 s0, s84, 0x80000
	s_addc_u32 s1, s85, 0
	s_add_i32 s79, s81, s30
	global_load_lds_dwordx4 v178, s[84:85]
	s_mov_b32 m0, s79
	s_nop 0
	global_load_lds_dwordx4 v182, s[0:1]
	s_add_i32 m0, s79, 0x2000
	s_nop 0
	global_load_lds_dwordx4 v178, s[0:1]
	s_mov_b32 m0, s44
	s_nop 0
	global_load_lds_dwordx4 v174, s[86:87]
	s_mov_b32 m0, s45
	s_nop 0
	global_load_lds_dwordx4 v176, s[86:87]
	s_waitcnt vmcnt(8)
	s_waitcnt lgkmcnt(0)
	s_setprio 1
	s_barrier
	v_mfma_f32_16x16x32_bf16 v[62:65], v[90:93], v[162:165], v[62:65]
	v_mfma_f32_16x16x32_bf16 v[62:65], v[94:97], v[166:169], v[62:65]
	v_mfma_f32_16x16x32_bf16 v[46:49], v[90:93], v[184:187], v[46:49]
	v_mfma_f32_16x16x32_bf16 v[46:49], v[94:97], v[190:193], v[46:49]
	v_mfma_f32_16x16x32_bf16 v[30:33], v[90:93], v[194:197], v[30:33]
	v_mfma_f32_16x16x32_bf16 v[30:33], v[94:97], v[198:201], v[30:33]
	v_mfma_f32_16x16x32_bf16 v[14:17], v[90:93], v[202:205], v[14:17]
	v_mfma_f32_16x16x32_bf16 v[14:17], v[94:97], v[206:209], v[14:17]
	v_mfma_f32_16x16x32_bf16 v[58:61], v[98:101], v[162:165], v[58:61]
	v_mfma_f32_16x16x32_bf16 v[58:61], v[102:105], v[166:169], v[58:61]
	v_mfma_f32_16x16x32_bf16 v[42:45], v[98:101], v[184:187], v[42:45]
	v_mfma_f32_16x16x32_bf16 v[42:45], v[102:105], v[190:193], v[42:45]
	v_mfma_f32_16x16x32_bf16 v[26:29], v[98:101], v[194:197], v[26:29]
	v_mfma_f32_16x16x32_bf16 v[26:29], v[102:105], v[198:201], v[26:29]
	v_mfma_f32_16x16x32_bf16 v[10:13], v[98:101], v[202:205], v[10:13]
	v_mfma_f32_16x16x32_bf16 v[10:13], v[102:105], v[206:209], v[10:13]
	v_mfma_f32_16x16x32_bf16 v[54:57], v[146:149], v[162:165], v[54:57]
	v_mfma_f32_16x16x32_bf16 v[54:57], v[150:153], v[166:169], v[54:57]
	v_mfma_f32_16x16x32_bf16 v[38:41], v[146:149], v[184:187], v[38:41]
	v_mfma_f32_16x16x32_bf16 v[38:41], v[150:153], v[190:193], v[38:41]
	v_mfma_f32_16x16x32_bf16 v[22:25], v[146:149], v[194:197], v[22:25]
	v_mfma_f32_16x16x32_bf16 v[22:25], v[150:153], v[198:201], v[22:25]
	v_mfma_f32_16x16x32_bf16 v[6:9], v[146:149], v[202:205], v[6:9]
	v_mfma_f32_16x16x32_bf16 v[6:9], v[150:153], v[206:209], v[6:9]
	v_mfma_f32_16x16x32_bf16 v[50:53], v[154:157], v[162:165], v[50:53]
	v_mfma_f32_16x16x32_bf16 v[50:53], v[158:161], v[166:169], v[50:53]
	v_mfma_f32_16x16x32_bf16 v[34:37], v[154:157], v[184:187], v[34:37]
	v_mfma_f32_16x16x32_bf16 v[34:37], v[158:161], v[190:193], v[34:37]
	v_mfma_f32_16x16x32_bf16 v[18:21], v[154:157], v[194:197], v[18:21]
	v_mfma_f32_16x16x32_bf16 v[18:21], v[158:161], v[198:201], v[18:21]
	v_mfma_f32_16x16x32_bf16 v[2:5], v[154:157], v[202:205], v[2:5]
	v_mfma_f32_16x16x32_bf16 v[2:5], v[158:161], v[206:209], v[2:5]
	s_barrier
; #define PG8_STAGE(bufoff, gbase, voff) do { _Pragma("unroll") for (int _i = 0; _i < 2; ++_i) \
;         __builtin_amdgcn_global_load_lds((const unsigned*)((const char*)(gbase) + (voff)[_i]), (PG8_LAS unsigned*)(lds + (bufoff) + ldsw + _i * 8192), 16, 0, 0); } while (0)
; #define PG8_LDA(dst, b, h) do { _Pragma("unroll") for (int m = 0; m < 4; ++m) _Pragma("unroll") for (int k = 0; k < 2; ++k) dst[m][k] = *(const PG8_LAS bf16x8*)(lds + PG8_SA(b, h) + aoff + m * 2048 + k * 1024); } while (0)
; #define PG8_LDB(dst, b, h) do { _Pragma("unroll") for (int n = 0; n < 2; ++n) _Pragma("unroll") for (int k = 0; k < 2; ++k) dst[n][k] = *(const PG8_LAS bf16x8*)(lds + PG8_SB(b, h) + boff + n * 2048 + k * 1024); } while (0)
; #define PG8_WAIT_V(n) asm volatile("s_waitcnt vmcnt(" #n ")" ::: "memory")
; #define PG8_WAIT_L(n) asm volatile("s_waitcnt lgkmcnt(" #n ")" ::: "memory")
; #define PG8_WAIT_V_SEL(sel) asm volatile("s_cmp_eq_u32 %0, 0\n\ts_cbranch_scc1 .Lw8_%=\n\ts_waitcnt vmcnt(22)\n\ts_branch .Lwd_%=\n.Lw8_%=:\n\ts_waitcnt vmcnt(8)\n.Lwd_%=:" :: "s"(sel) : "memory", "scc")
; #define PG8_BAR __builtin_amdgcn_s_barrier()
; #define PG8_SCHED __builtin_amdgcn_sched_barrier(0)
;     ...
;             PG8_LDB(B0, 0, 0); PG8_LDB(B1, 0, 1); PG8_SCHED; PG8_LDA(At, 0, 0); PG8_STAGE(PG8_SA(1, 1), a1 + hstep, voffA);
;             PG8_WAIT_V_SEL(relax);
;             PG8_WAIT_L(0); PG8_BAR; PG8_MMA(0, 0, At, B0); PG8_MMA(0, 1, At, B1); PG8_BAR; PG8_SCHED;
;             PG8_LDA(At, 0, 1); PG8_STAGE(PG8_SB(0, 0), b2, voffB); PG8_STAGE(PG8_SB(0, 1), b2 + hstep, voffB); PG8_STAGE(PG8_SA(0, 0), a2, voffA);
;             PG8_WAIT_V_SEL(relax);
;             PG8_WAIT_L(0); PG8_BAR; PG8_MMA(1, 0, At, B0); PG8_MMA(1, 1, At, B1); PG8_BAR; PG8_SCHED;
;             PG8_LDB(B0, 1, 0); PG8_LDB(B1, 1, 1); PG8_SCHED; PG8_LDA(At, 1, 0); PG8_STAGE(PG8_SA(0, 1), a2 + hstep, voffA);
;             PG8_WAIT_V(8); PG8_WAIT_L(0); PG8_BAR; PG8_MMA(0, 0, At, B0); PG8_MMA(0, 1, At, B1); PG8_BAR; PG8_SCHED;
;             PG8_LDA(At, 1, 1); PG8_STAGE(PG8_SB(1, 0), b3, voffB); PG8_STAGE(PG8_SB(1, 1), b3 + hstep, voffB); PG8_STAGE(PG8_SA(1, 0), a3, voffA);
;             PG8_WAIT_V(8); PG8_WAIT_L(0); PG8_BAR; PG8_MMA(1, 0, At, B0); PG8_MMA(1, 1, At, B1); PG8_BAR; PG8_SCHED;
	s_setprio 0
	s_add_i32 s79, 0, 0x18000
	s_add_i32 s81, 0, 0x1c000
	ds_read_b128 v[90:93], v210 offset:32768
	ds_read_b128 v[94:97], v210 offset:33792
	ds_read_b128 v[98:101], v210 offset:34816
	ds_read_b128 v[102:105], v210 offset:35840
	ds_read_b128 v[146:149], v210 offset:49152
	ds_read_b128 v[150:153], v210 offset:50176
	ds_read_b128 v[154:157], v210 offset:51200
	ds_read_b128 v[158:161], v210 offset:52224
	s_add_u32 s0, s86, 0x80000
	s_addc_u32 s1, s87, 0
	s_mov_b32 m0, s46
	ds_read_b128 v[162:165], v230 offset:32768
	ds_read_b128 v[166:169], v230 offset:33792
	ds_read_b128 v[184:187], v230 offset:34816
	ds_read_b128 v[190:193], v230 offset:35840
	ds_read_b128 v[194:197], v230 offset:36864
	ds_read_b128 v[198:201], v230 offset:37888
	ds_read_b128 v[202:205], v230 offset:38912
	ds_read_b128 v[206:209], v230 offset:39936
	global_load_lds_dwordx4 v174, s[0:1]
	s_mov_b32 m0, s47
	s_nop 0
	global_load_lds_dwordx4 v176, s[0:1]
	s_waitcnt vmcnt(8)
	s_waitcnt lgkmcnt(0)
	s_setprio 1
	s_barrier
	v_mfma_f32_16x16x32_bf16 v[142:145], v[90:93], v[162:165], v[142:145]
	v_mfma_f32_16x16x32_bf16 v[142:145], v[94:97], v[166:169], v[142:145]
	v_mfma_f32_16x16x32_bf16 v[126:129], v[90:93], v[184:187], v[126:129]
	v_mfma_f32_16x16x32_bf16 v[126:129], v[94:97], v[190:193], v[126:129]
	v_mfma_f32_16x16x32_bf16 v[110:113], v[90:93], v[194:197], v[110:113]
	v_mfma_f32_16x16x32_bf16 v[110:113], v[94:97], v[198:201], v[110:113]
	v_mfma_f32_16x16x32_bf16 v[78:81], v[90:93], v[202:205], v[78:81]
	v_mfma_f32_16x16x32_bf16 v[78:81], v[94:97], v[206:209], v[78:81]
	v_mfma_f32_16x16x32_bf16 v[138:141], v[98:101], v[162:165], v[138:141]
	v_mfma_f32_16x16x32_bf16 v[138:141], v[102:105], v[166:169], v[138:141]
	v_mfma_f32_16x16x32_bf16 v[122:125], v[98:101], v[184:187], v[122:125]
	v_mfma_f32_16x16x32_bf16 v[122:125], v[102:105], v[190:193], v[122:125]
	v_mfma_f32_16x16x32_bf16 v[106:109], v[98:101], v[194:197], v[106:109]
	v_mfma_f32_16x16x32_bf16 v[106:109], v[102:105], v[198:201], v[106:109]
	v_mfma_f32_16x16x32_bf16 v[74:77], v[98:101], v[202:205], v[74:77]
	v_mfma_f32_16x16x32_bf16 v[74:77], v[102:105], v[206:209], v[74:77]
	v_mfma_f32_16x16x32_bf16 v[134:137], v[146:149], v[162:165], v[134:137]
	v_mfma_f32_16x16x32_bf16 v[134:137], v[150:153], v[166:169], v[134:137]
	v_mfma_f32_16x16x32_bf16 v[118:121], v[146:149], v[184:187], v[118:121]
	v_mfma_f32_16x16x32_bf16 v[118:121], v[150:153], v[190:193], v[118:121]
	v_mfma_f32_16x16x32_bf16 v[86:89], v[146:149], v[194:197], v[86:89]
	v_mfma_f32_16x16x32_bf16 v[86:89], v[150:153], v[198:201], v[86:89]
	v_mfma_f32_16x16x32_bf16 v[70:73], v[146:149], v[202:205], v[70:73]
	v_mfma_f32_16x16x32_bf16 v[70:73], v[150:153], v[206:209], v[70:73]
	v_mfma_f32_16x16x32_bf16 v[130:133], v[154:157], v[162:165], v[130:133]
	v_mfma_f32_16x16x32_bf16 v[130:133], v[158:161], v[166:169], v[130:133]
	v_mfma_f32_16x16x32_bf16 v[114:117], v[154:157], v[184:187], v[114:117]
	v_mfma_f32_16x16x32_bf16 v[114:117], v[158:161], v[190:193], v[114:117]
	v_mfma_f32_16x16x32_bf16 v[82:85], v[154:157], v[194:197], v[82:85]
	v_mfma_f32_16x16x32_bf16 v[82:85], v[158:161], v[198:201], v[82:85]
	v_mfma_f32_16x16x32_bf16 v[66:69], v[154:157], v[202:205], v[66:69]
	v_mfma_f32_16x16x32_bf16 v[66:69], v[158:161], v[206:209], v[66:69]
	s_barrier
	s_setprio 0
	s_add_i32 s0, s79, s30
	s_mov_b32 m0, s0
	ds_read_b128 v[162:165], v230 offset:49152
	ds_read_b128 v[166:169], v230 offset:50176
	ds_read_b128 v[184:187], v230 offset:51200
	ds_read_b128 v[190:193], v230 offset:52224
	ds_read_b128 v[194:197], v230 offset:53248
	ds_read_b128 v[198:201], v230 offset:54272
	ds_read_b128 v[202:205], v230 offset:55296
	ds_read_b128 v[206:209], v230 offset:56320
	s_add_u32 s100, s84, 0x80
	s_addc_u32 s101, s85, 0
	global_load_lds_dwordx4 v182, s[100:101]
	s_add_i32 m0, s0, 0x2000
	s_add_u32 s0, s84, 0x80080
	s_addc_u32 s1, s85, 0
	s_add_i32 s79, s81, s30
	global_load_lds_dwordx4 v178, s[100:101]
	s_mov_b32 m0, s79
	s_nop 0
	global_load_lds_dwordx4 v182, s[0:1]
	s_add_i32 m0, s79, 0x2000
	s_nop 0
	global_load_lds_dwordx4 v178, s[0:1]
	s_mov_b32 m0, s49
	s_nop 0
	s_add_u32 s100, s86, 0x80
	s_addc_u32 s101, s87, 0
	global_load_lds_dwordx4 v174, s[100:101]
	s_mov_b32 m0, s50
	s_nop 0
	global_load_lds_dwordx4 v176, s[100:101]
	s_waitcnt vmcnt(8)
	s_waitcnt lgkmcnt(0)
	s_setprio 1
	s_barrier
	v_mfma_f32_16x16x32_bf16 v[62:65], v[90:93], v[162:165], v[62:65]
	v_mfma_f32_16x16x32_bf16 v[62:65], v[94:97], v[166:169], v[62:65]
	v_mfma_f32_16x16x32_bf16 v[46:49], v[90:93], v[184:187], v[46:49]
	v_mfma_f32_16x16x32_bf16 v[46:49], v[94:97], v[190:193], v[46:49]
	v_mfma_f32_16x16x32_bf16 v[30:33], v[90:93], v[194:197], v[30:33]
	v_mfma_f32_16x16x32_bf16 v[30:33], v[94:97], v[198:201], v[30:33]
	v_mfma_f32_16x16x32_bf16 v[14:17], v[90:93], v[202:205], v[14:17]
	v_mfma_f32_16x16x32_bf16 v[14:17], v[94:97], v[206:209], v[14:17]
	v_mfma_f32_16x16x32_bf16 v[58:61], v[98:101], v[162:165], v[58:61]
	v_mfma_f32_16x16x32_bf16 v[58:61], v[102:105], v[166:169], v[58:61]
	v_mfma_f32_16x16x32_bf16 v[42:45], v[98:101], v[184:187], v[42:45]
	v_mfma_f32_16x16x32_bf16 v[42:45], v[102:105], v[190:193], v[42:45]
	v_mfma_f32_16x16x32_bf16 v[26:29], v[98:101], v[194:197], v[26:29]
	v_mfma_f32_16x16x32_bf16 v[26:29], v[102:105], v[198:201], v[26:29]
	v_mfma_f32_16x16x32_bf16 v[10:13], v[98:101], v[202:205], v[10:13]
	v_mfma_f32_16x16x32_bf16 v[10:13], v[102:105], v[206:209], v[10:13]
	v_mfma_f32_16x16x32_bf16 v[54:57], v[146:149], v[162:165], v[54:57]
	v_mfma_f32_16x16x32_bf16 v[54:57], v[150:153], v[166:169], v[54:57]
	v_mfma_f32_16x16x32_bf16 v[38:41], v[146:149], v[184:187], v[38:41]
	v_mfma_f32_16x16x32_bf16 v[38:41], v[150:153], v[190:193], v[38:41]
	v_mfma_f32_16x16x32_bf16 v[22:25], v[146:149], v[194:197], v[22:25]
	v_mfma_f32_16x16x32_bf16 v[22:25], v[150:153], v[198:201], v[22:25]
	v_mfma_f32_16x16x32_bf16 v[6:9], v[146:149], v[202:205], v[6:9]
	v_mfma_f32_16x16x32_bf16 v[6:9], v[150:153], v[206:209], v[6:9]
	v_mfma_f32_16x16x32_bf16 v[50:53], v[154:157], v[162:165], v[50:53]
	v_mfma_f32_16x16x32_bf16 v[50:53], v[158:161], v[166:169], v[50:53]
	v_mfma_f32_16x16x32_bf16 v[34:37], v[154:157], v[184:187], v[34:37]
	v_mfma_f32_16x16x32_bf16 v[34:37], v[158:161], v[190:193], v[34:37]
	v_mfma_f32_16x16x32_bf16 v[18:21], v[154:157], v[194:197], v[18:21]
	v_mfma_f32_16x16x32_bf16 v[18:21], v[158:161], v[198:201], v[18:21]
	v_mfma_f32_16x16x32_bf16 v[2:5], v[154:157], v[202:205], v[2:5]
	v_mfma_f32_16x16x32_bf16 v[2:5], v[158:161], v[206:209], v[2:5]
	s_barrier
	s_setprio 0
	s_add_i32 s73, s73, 2
	s_add_u32 s82, s82, 0x100
	s_addc_u32 s83, s83, 0
	s_add_u32 s59, s59, 0x100
	s_addc_u32 s71, s71, 0
	s_cmp_gt_u32 s73, 29
	s_cbranch_scc0 .LBB0_541
	s_and_b64 vcc, exec, s[68:69]
	s_cbranch_vccz .LBB0_544
	s_barrier

; #define PG8_STAGE(bufoff, gbase, voff) do { _Pragma("unroll") for (int _i = 0; _i < 2; ++_i) \
;         __builtin_amdgcn_global_load_lds((const unsigned*)((const char*)(gbase) + (voff)[_i]), (PG8_LAS unsigned*)(lds + (bufoff) + ldsw + _i * 8192), 16, 0, 0); } while (0)
; #define PG8_LDA(dst, b, h) do { _Pragma("unroll") for (int m = 0; m < 4; ++m) _Pragma("unroll") for (int k = 0; k < 2; ++k) dst[m][k] = *(const PG8_LAS bf16x8*)(lds + PG8_SA(b, h) + aoff + m * 2048 + k * 1024); } while (0)
; #define PG8_LDB(dst, b, h) do { _Pragma("unroll") for (int n = 0; n < 2; ++n) _Pragma("unroll") for (int k = 0; k < 2; ++k) dst[n][k] = *(const PG8_LAS bf16x8*)(lds + PG8_SB(b, h) + boff + n * 2048 + k * 1024); } while (0)
; #define PG8_WAIT_L(n) asm volatile("s_waitcnt lgkmcnt(" #n ")" ::: "memory")
; #define PG8_WAIT_V_SEL(sel) asm volatile("s_cmp_eq_u32 %0, 0\n\ts_cbranch_scc1 .Lw8_%=\n\ts_waitcnt vmcnt(22)\n\ts_branch .Lwd_%=\n.Lw8_%=:\n\ts_waitcnt vmcnt(8)\n.Lwd_%=:" :: "s"(sel) : "memory", "scc")
; #define PG8_BAR __builtin_amdgcn_s_barrier()
; #define PG8_SCHED __builtin_amdgcn_sched_barrier(0)
;     ...
;         for (int t = 0; t < nt * KREP; t += 2) {
;             const bool last = (t == nt * KREP - 2);
;             const int t1w = KREP > 1 ? ((t + 1) & (nt - 1)) : t + 1, t2w = KREP > 1 ? ((t + 2) & (nt - 1)) : t + 2;
;             const char* a1 = cA + (size_t)t1w * kstep;
;             const char* a2 = last ? nA : cA + (size_t)t2w * kstep; const char* b2 = last ? nB : cB + (size_t)t2w * kstep;
;             const char* a3 = a2 + kstep; const char* b3 = b2 + kstep;
;             if (last && has_next) S.a_ready(nxt);
;             const int relax = __builtin_amdgcn_readfirstlane((MK_RELAXW && t == 0 && ui > 0) ? 1 : 0);
;             if constexpr (SP2) {
;             PG8_LDB(B0, 0, 0); PG8_LDB(B1, 0, 1); PG8_SCHED; PG8_LDA(At, 0, 0); PG8_STAGE(PG8_SA(1, 1), a1 + hstep, voffA);
;             PG8_WAIT_V_SEL(relax);
;             PG8_WAIT_L(0); PG8_BAR; PG8_MMA(0, 0, At, B0); PG8_MMA(0, 1, At, B1); PG8_BAR; PG8_SCHED;
;             PG8_LDA(At, 0, 1); PG8_STAGE(PG8_SB(0, 0), b2, voffB); PG8_STAGE(PG8_SB(0, 1), b2 + hstep, voffB); PG8_STAGE(PG8_SA(0, 0), a2, voffA);
;             PG8_WAIT_V_SEL(relax);
;             PG8_WAIT_L(0); PG8_BAR; PG8_MMA(1, 0, At, B0); PG8_MMA(1, 1, At, B1); PG8_BAR; PG8_SCHED;
.LBB0_596:
	s_add_u32 s0, s74, 0xfff80080
	s_addc_u32 s1, s75, -1
	s_add_i32 s83, 0, 0x10000
	s_cmp_eq_u32 s82, 28
	s_cselect_b32 s79, s40, s1
	s_cselect_b32 s78, s41, s0
	s_cselect_b32 s77, s65, s81
	s_cselect_b32 s76, s73, s80
	s_add_i32 s84, 0, 0x14000
	ds_read_b128 v[150:153], v180
	ds_read_b128 v[154:157], v180 offset:1024
	ds_read_b128 v[158:161], v180 offset:2048
	ds_read_b128 v[162:165], v180 offset:3072
	ds_read_b128 v[166:169], v180 offset:16384
	ds_read_b128 v[172:175], v180 offset:17408
	ds_read_b128 v[176:179], v180 offset:18432
	ds_read_b128 v[188:191], v180 offset:19456
	s_add_i32 m0, s35, 0xc000
	ds_read_b128 v[192:195], v148
	ds_read_b128 v[196:199], v148 offset:1024
	ds_read_b128 v[200:203], v148 offset:2048
	ds_read_b128 v[204:207], v148 offset:3072
	ds_read_b128 v[208:211], v148 offset:4096
	ds_read_b128 v[212:215], v148 offset:5120
	ds_read_b128 v[216:219], v148 offset:6144
	ds_read_b128 v[220:223], v148 offset:7168
	global_load_lds_dwordx4 v140, s[74:75]
	s_add_i32 m0, s35, 0xe000
	s_nop 0
	global_load_lds_dwordx4 v142, s[74:75]
	s_waitcnt vmcnt(8)
	s_waitcnt lgkmcnt(0)
	s_setprio 1
	s_barrier
	v_mfma_f32_16x16x32_bf16 v[126:129], v[150:153], v[192:195], v[126:129]
	v_mfma_f32_16x16x32_bf16 v[126:129], v[154:157], v[196:199], v[126:129]
	v_mfma_f32_16x16x32_bf16 v[122:125], v[150:153], v[200:203], v[122:125]
	v_mfma_f32_16x16x32_bf16 v[122:125], v[154:157], v[204:207], v[122:125]
	v_mfma_f32_16x16x32_bf16 v[118:121], v[150:153], v[208:211], v[118:121]
	v_mfma_f32_16x16x32_bf16 v[118:121], v[154:157], v[212:215], v[118:121]
	v_mfma_f32_16x16x32_bf16 v[114:117], v[150:153], v[216:219], v[114:117]
	v_mfma_f32_16x16x32_bf16 v[114:117], v[154:157], v[220:223], v[114:117]
	v_mfma_f32_16x16x32_bf16 v[110:113], v[158:161], v[192:195], v[110:113]
	v_mfma_f32_16x16x32_bf16 v[110:113], v[162:165], v[196:199], v[110:113]
	v_mfma_f32_16x16x32_bf16 v[106:109], v[158:161], v[200:203], v[106:109]
	v_mfma_f32_16x16x32_bf16 v[106:109], v[162:165], v[204:207], v[106:109]
	v_mfma_f32_16x16x32_bf16 v[102:105], v[158:161], v[208:211], v[102:105]
	v_mfma_f32_16x16x32_bf16 v[102:105], v[162:165], v[212:215], v[102:105]
	v_mfma_f32_16x16x32_bf16 v[98:101], v[158:161], v[216:219], v[98:101]
	v_mfma_f32_16x16x32_bf16 v[98:101], v[162:165], v[220:223], v[98:101]
	v_mfma_f32_16x16x32_bf16 v[70:73], v[166:169], v[192:195], v[70:73]
	v_mfma_f32_16x16x32_bf16 v[70:73], v[172:175], v[196:199], v[70:73]
	v_mfma_f32_16x16x32_bf16 v[66:69], v[166:169], v[200:203], v[66:69]
	v_mfma_f32_16x16x32_bf16 v[66:69], v[172:175], v[204:207], v[66:69]
	v_mfma_f32_16x16x32_bf16 v[58:61], v[166:169], v[208:211], v[58:61]
	v_mfma_f32_16x16x32_bf16 v[58:61], v[172:175], v[212:215], v[58:61]
	v_mfma_f32_16x16x32_bf16 v[46:49], v[166:169], v[216:219], v[46:49]
	v_mfma_f32_16x16x32_bf16 v[46:49], v[172:175], v[220:223], v[46:49]
	v_mfma_f32_16x16x32_bf16 v[50:53], v[176:179], v[192:195], v[50:53]
	v_mfma_f32_16x16x32_bf16 v[50:53], v[188:191], v[196:199], v[50:53]
	v_mfma_f32_16x16x32_bf16 v[42:45], v[176:179], v[200:203], v[42:45]
	v_mfma_f32_16x16x32_bf16 v[42:45], v[188:191], v[204:207], v[42:45]
	v_mfma_f32_16x16x32_bf16 v[38:41], v[176:179], v[208:211], v[38:41]
	v_mfma_f32_16x16x32_bf16 v[38:41], v[188:191], v[212:215], v[38:41]
	v_mfma_f32_16x16x32_bf16 v[34:37], v[176:179], v[216:219], v[34:37]
	v_mfma_f32_16x16x32_bf16 v[34:37], v[188:191], v[220:223], v[34:37]
	s_barrier
	s_setprio 0
	s_add_i32 s0, s83, s20
	s_mov_b32 m0, s0
	ds_read_b128 v[192:195], v148 offset:16384
	ds_read_b128 v[196:199], v148 offset:17408
	ds_read_b128 v[200:203], v148 offset:18432
	ds_read_b128 v[204:207], v148 offset:19456
	ds_read_b128 v[208:211], v148 offset:20480
	ds_read_b128 v[212:215], v148 offset:21504
	ds_read_b128 v[216:219], v148 offset:22528
	ds_read_b128 v[220:223], v148 offset:23552
	global_load_lds_dwordx4 v132, s[76:77]
	s_add_i32 m0, s0, 0x2000
	s_add_u32 s0, s76, 0x80000
	s_addc_u32 s1, s77, 0
	s_add_i32 s83, s84, s20
	global_load_lds_dwordx4 v136, s[76:77]
	s_mov_b32 m0, s83
	s_nop 0
	global_load_lds_dwordx4 v132, s[0:1]
	s_add_i32 m0, s83, 0x2000
	s_nop 0
	global_load_lds_dwordx4 v136, s[0:1]
	s_mov_b32 m0, s35
	s_nop 0
	global_load_lds_dwordx4 v130, s[78:79]
	s_mov_b32 m0, s37
	s_nop 0
	global_load_lds_dwordx4 v134, s[78:79]
	s_waitcnt vmcnt(8)
	s_waitcnt lgkmcnt(0)
	s_setprio 1
	s_barrier
	v_mfma_f32_16x16x32_bf16 v[94:97], v[150:153], v[192:195], v[94:97]
	v_mfma_f32_16x16x32_bf16 v[94:97], v[154:157], v[196:199], v[94:97]
	v_mfma_f32_16x16x32_bf16 v[90:93], v[150:153], v[200:203], v[90:93]
	v_mfma_f32_16x16x32_bf16 v[90:93], v[154:157], v[204:207], v[90:93]
	v_mfma_f32_16x16x32_bf16 v[86:89], v[150:153], v[208:211], v[86:89]
	v_mfma_f32_16x16x32_bf16 v[86:89], v[154:157], v[212:215], v[86:89]
	v_mfma_f32_16x16x32_bf16 v[82:85], v[150:153], v[216:219], v[82:85]
	v_mfma_f32_16x16x32_bf16 v[82:85], v[154:157], v[220:223], v[82:85]
	v_mfma_f32_16x16x32_bf16 v[78:81], v[158:161], v[192:195], v[78:81]
	v_mfma_f32_16x16x32_bf16 v[78:81], v[162:165], v[196:199], v[78:81]
	v_mfma_f32_16x16x32_bf16 v[74:77], v[158:161], v[200:203], v[74:77]
	v_mfma_f32_16x16x32_bf16 v[74:77], v[162:165], v[204:207], v[74:77]
	v_mfma_f32_16x16x32_bf16 v[62:65], v[158:161], v[208:211], v[62:65]
	v_mfma_f32_16x16x32_bf16 v[62:65], v[162:165], v[212:215], v[62:65]
	v_mfma_f32_16x16x32_bf16 v[54:57], v[158:161], v[216:219], v[54:57]
	v_mfma_f32_16x16x32_bf16 v[54:57], v[162:165], v[220:223], v[54:57]
	v_mfma_f32_16x16x32_bf16 v[30:33], v[166:169], v[192:195], v[30:33]
	v_mfma_f32_16x16x32_bf16 v[30:33], v[172:175], v[196:199], v[30:33]
	v_mfma_f32_16x16x32_bf16 v[26:29], v[166:169], v[200:203], v[26:29]
	v_mfma_f32_16x16x32_bf16 v[26:29], v[172:175], v[204:207], v[26:29]
	v_mfma_f32_16x16x32_bf16 v[22:25], v[166:169], v[208:211], v[22:25]
	v_mfma_f32_16x16x32_bf16 v[22:25], v[172:175], v[212:215], v[22:25]
	v_mfma_f32_16x16x32_bf16 v[18:21], v[166:169], v[216:219], v[18:21]
	v_mfma_f32_16x16x32_bf16 v[18:21], v[172:175], v[220:223], v[18:21]
	v_mfma_f32_16x16x32_bf16 v[14:17], v[176:179], v[192:195], v[14:17]
	v_mfma_f32_16x16x32_bf16 v[14:17], v[188:191], v[196:199], v[14:17]
	v_mfma_f32_16x16x32_bf16 v[10:13], v[176:179], v[200:203], v[10:13]
	v_mfma_f32_16x16x32_bf16 v[10:13], v[188:191], v[204:207], v[10:13]
	v_mfma_f32_16x16x32_bf16 v[6:9], v[176:179], v[208:211], v[6:9]
	v_mfma_f32_16x16x32_bf16 v[6:9], v[188:191], v[212:215], v[6:9]
	v_mfma_f32_16x16x32_bf16 v[2:5], v[176:179], v[216:219], v[2:5]
	v_mfma_f32_16x16x32_bf16 v[2:5], v[188:191], v[220:223], v[2:5]
	s_barrier
; #define PG8_STAGE(bufoff, gbase, voff) do { _Pragma("unroll") for (int _i = 0; _i < 2; ++_i) \
;         __builtin_amdgcn_global_load_lds((const unsigned*)((const char*)(gbase) + (voff)[_i]), (PG8_LAS unsigned*)(lds + (bufoff) + ldsw + _i * 8192), 16, 0, 0); } while (0)
; #define PG8_LDA(dst, b, h) do { _Pragma("unroll") for (int m = 0; m < 4; ++m) _Pragma("unroll") for (int k = 0; k < 2; ++k) dst[m][k] = *(const PG8_LAS bf16x8*)(lds + PG8_SA(b, h) + aoff + m * 2048 + k * 1024); } while (0)
; #define PG8_LDB(dst, b, h) do { _Pragma("unroll") for (int n = 0; n < 2; ++n) _Pragma("unroll") for (int k = 0; k < 2; ++k) dst[n][k] = *(const PG8_LAS bf16x8*)(lds + PG8_SB(b, h) + boff + n * 2048 + k * 1024); } while (0)
; #define PG8_WAIT_V(n) asm volatile("s_waitcnt vmcnt(" #n ")" ::: "memory")
; #define PG8_WAIT_L(n) asm volatile("s_waitcnt lgkmcnt(" #n ")" ::: "memory")
; #define PG8_WAIT_V_SEL(sel) asm volatile("s_cmp_eq_u32 %0, 0\n\ts_cbranch_scc1 .Lw8_%=\n\ts_waitcnt vmcnt(22)\n\ts_branch .Lwd_%=\n.Lw8_%=:\n\ts_waitcnt vmcnt(8)\n.Lwd_%=:" :: "s"(sel) : "memory", "scc")
; #define PG8_BAR __builtin_amdgcn_s_barrier()
; #define PG8_SCHED __builtin_amdgcn_sched_barrier(0)
;     ...
;             PG8_LDB(B0, 0, 0); PG8_LDB(B1, 0, 1); PG8_SCHED; PG8_LDA(At, 0, 0); PG8_STAGE(PG8_SA(1, 1), a1 + hstep, voffA);
;             PG8_WAIT_V_SEL(relax);
;             PG8_WAIT_L(0); PG8_BAR; PG8_MMA(0, 0, At, B0); PG8_MMA(0, 1, At, B1); PG8_BAR; PG8_SCHED;
;             PG8_LDA(At, 0, 1); PG8_STAGE(PG8_SB(0, 0), b2, voffB); PG8_STAGE(PG8_SB(0, 1), b2 + hstep, voffB); PG8_STAGE(PG8_SA(0, 0), a2, voffA);
;             PG8_WAIT_V_SEL(relax);
;             PG8_WAIT_L(0); PG8_BAR; PG8_MMA(1, 0, At, B0); PG8_MMA(1, 1, At, B1); PG8_BAR; PG8_SCHED;
;             PG8_LDB(B0, 1, 0); PG8_LDB(B1, 1, 1); PG8_SCHED; PG8_LDA(At, 1, 0); PG8_STAGE(PG8_SA(0, 1), a2 + hstep, voffA);
;             PG8_WAIT_V(8); PG8_WAIT_L(0); PG8_BAR; PG8_MMA(0, 0, At, B0); PG8_MMA(0, 1, At, B1); PG8_BAR; PG8_SCHED;
;             PG8_LDA(At, 1, 1); PG8_STAGE(PG8_SB(1, 0), b3, voffB); PG8_STAGE(PG8_SB(1, 1), b3 + hstep, voffB); PG8_STAGE(PG8_SA(1, 0), a3, voffA);
;             PG8_WAIT_V(8); PG8_WAIT_L(0); PG8_BAR; PG8_MMA(1, 0, At, B0); PG8_MMA(1, 1, At, B1); PG8_BAR; PG8_SCHED;
	s_setprio 0
	s_add_i32 s83, 0, 0x18000
	s_add_i32 s84, 0, 0x1c000
	ds_read_b128 v[150:153], v180 offset:32768
	ds_read_b128 v[154:157], v180 offset:33792
	ds_read_b128 v[158:161], v180 offset:34816
	ds_read_b128 v[162:165], v180 offset:35840
	ds_read_b128 v[166:169], v180 offset:49152
	ds_read_b128 v[172:175], v180 offset:50176
	ds_read_b128 v[176:179], v180 offset:51200
	ds_read_b128 v[188:191], v180 offset:52224
	s_add_u32 s0, s78, 0x80000
	s_addc_u32 s1, s79, 0
	s_mov_b32 m0, s43
	ds_read_b128 v[192:195], v148 offset:32768
	ds_read_b128 v[196:199], v148 offset:33792
	ds_read_b128 v[200:203], v148 offset:34816
	ds_read_b128 v[204:207], v148 offset:35840
	ds_read_b128 v[208:211], v148 offset:36864
	ds_read_b128 v[212:215], v148 offset:37888
	ds_read_b128 v[216:219], v148 offset:38912
	ds_read_b128 v[220:223], v148 offset:39936
	global_load_lds_dwordx4 v130, s[0:1]
	s_mov_b32 m0, s44
	s_nop 0
	global_load_lds_dwordx4 v134, s[0:1]
	s_waitcnt vmcnt(8)
	s_waitcnt lgkmcnt(0)
	s_setprio 1
	s_barrier
	v_mfma_f32_16x16x32_bf16 v[126:129], v[150:153], v[192:195], v[126:129]
	v_mfma_f32_16x16x32_bf16 v[126:129], v[154:157], v[196:199], v[126:129]
	v_mfma_f32_16x16x32_bf16 v[122:125], v[150:153], v[200:203], v[122:125]
	v_mfma_f32_16x16x32_bf16 v[122:125], v[154:157], v[204:207], v[122:125]
	v_mfma_f32_16x16x32_bf16 v[118:121], v[150:153], v[208:211], v[118:121]
	v_mfma_f32_16x16x32_bf16 v[118:121], v[154:157], v[212:215], v[118:121]
	v_mfma_f32_16x16x32_bf16 v[114:117], v[150:153], v[216:219], v[114:117]
	v_mfma_f32_16x16x32_bf16 v[114:117], v[154:157], v[220:223], v[114:117]
	v_mfma_f32_16x16x32_bf16 v[110:113], v[158:161], v[192:195], v[110:113]
	v_mfma_f32_16x16x32_bf16 v[110:113], v[162:165], v[196:199], v[110:113]
	v_mfma_f32_16x16x32_bf16 v[106:109], v[158:161], v[200:203], v[106:109]
	v_mfma_f32_16x16x32_bf16 v[106:109], v[162:165], v[204:207], v[106:109]
	v_mfma_f32_16x16x32_bf16 v[102:105], v[158:161], v[208:211], v[102:105]
	v_mfma_f32_16x16x32_bf16 v[102:105], v[162:165], v[212:215], v[102:105]
	v_mfma_f32_16x16x32_bf16 v[98:101], v[158:161], v[216:219], v[98:101]
	v_mfma_f32_16x16x32_bf16 v[98:101], v[162:165], v[220:223], v[98:101]
	v_mfma_f32_16x16x32_bf16 v[70:73], v[166:169], v[192:195], v[70:73]
	v_mfma_f32_16x16x32_bf16 v[70:73], v[172:175], v[196:199], v[70:73]
	v_mfma_f32_16x16x32_bf16 v[66:69], v[166:169], v[200:203], v[66:69]
	v_mfma_f32_16x16x32_bf16 v[66:69], v[172:175], v[204:207], v[66:69]
	v_mfma_f32_16x16x32_bf16 v[58:61], v[166:169], v[208:211], v[58:61]
	v_mfma_f32_16x16x32_bf16 v[58:61], v[172:175], v[212:215], v[58:61]
	v_mfma_f32_16x16x32_bf16 v[46:49], v[166:169], v[216:219], v[46:49]
	v_mfma_f32_16x16x32_bf16 v[46:49], v[172:175], v[220:223], v[46:49]
	v_mfma_f32_16x16x32_bf16 v[50:53], v[176:179], v[192:195], v[50:53]
	v_mfma_f32_16x16x32_bf16 v[50:53], v[188:191], v[196:199], v[50:53]
	v_mfma_f32_16x16x32_bf16 v[42:45], v[176:179], v[200:203], v[42:45]
	v_mfma_f32_16x16x32_bf16 v[42:45], v[188:191], v[204:207], v[42:45]
	v_mfma_f32_16x16x32_bf16 v[38:41], v[176:179], v[208:211], v[38:41]
	v_mfma_f32_16x16x32_bf16 v[38:41], v[188:191], v[212:215], v[38:41]
	v_mfma_f32_16x16x32_bf16 v[34:37], v[176:179], v[216:219], v[34:37]
	v_mfma_f32_16x16x32_bf16 v[34:37], v[188:191], v[220:223], v[34:37]
	s_barrier
	s_setprio 0
	s_add_i32 s0, s83, s20
	s_mov_b32 m0, s0
	ds_read_b128 v[192:195], v148 offset:49152
	ds_read_b128 v[196:199], v148 offset:50176
	ds_read_b128 v[200:203], v148 offset:51200
	ds_read_b128 v[204:207], v148 offset:52224
	ds_read_b128 v[208:211], v148 offset:53248
	ds_read_b128 v[212:215], v148 offset:54272
	ds_read_b128 v[216:219], v148 offset:55296
	ds_read_b128 v[220:223], v148 offset:56320
	s_add_u32 s100, s76, 0x80
	s_addc_u32 s101, s77, 0
	global_load_lds_dwordx4 v132, s[100:101]
	s_add_i32 m0, s0, 0x2000
	s_add_u32 s0, s76, 0x80080
	s_addc_u32 s1, s77, 0
	s_add_i32 s76, s84, s20
	global_load_lds_dwordx4 v136, s[100:101]
	s_mov_b32 m0, s76
	s_nop 0
	global_load_lds_dwordx4 v132, s[0:1]
	s_add_i32 m0, s76, 0x2000
	s_nop 0
	global_load_lds_dwordx4 v136, s[0:1]
	s_mov_b32 m0, s48
	s_nop 0
	s_add_u32 s100, s78, 0x80
	s_addc_u32 s101, s79, 0
	global_load_lds_dwordx4 v130, s[100:101]
	s_mov_b32 m0, s49
	s_nop 0
	global_load_lds_dwordx4 v134, s[100:101]
	s_waitcnt vmcnt(8)
	s_waitcnt lgkmcnt(0)
	s_setprio 1
	s_barrier
	v_mfma_f32_16x16x32_bf16 v[94:97], v[150:153], v[192:195], v[94:97]
	v_mfma_f32_16x16x32_bf16 v[94:97], v[154:157], v[196:199], v[94:97]
	v_mfma_f32_16x16x32_bf16 v[90:93], v[150:153], v[200:203], v[90:93]
	v_mfma_f32_16x16x32_bf16 v[90:93], v[154:157], v[204:207], v[90:93]
	v_mfma_f32_16x16x32_bf16 v[86:89], v[150:153], v[208:211], v[86:89]
	v_mfma_f32_16x16x32_bf16 v[86:89], v[154:157], v[212:215], v[86:89]
	v_mfma_f32_16x16x32_bf16 v[82:85], v[150:153], v[216:219], v[82:85]
	v_mfma_f32_16x16x32_bf16 v[82:85], v[154:157], v[220:223], v[82:85]
	v_mfma_f32_16x16x32_bf16 v[78:81], v[158:161], v[192:195], v[78:81]
	v_mfma_f32_16x16x32_bf16 v[78:81], v[162:165], v[196:199], v[78:81]
	v_mfma_f32_16x16x32_bf16 v[74:77], v[158:161], v[200:203], v[74:77]
	v_mfma_f32_16x16x32_bf16 v[74:77], v[162:165], v[204:207], v[74:77]
	v_mfma_f32_16x16x32_bf16 v[62:65], v[158:161], v[208:211], v[62:65]
	v_mfma_f32_16x16x32_bf16 v[62:65], v[162:165], v[212:215], v[62:65]
	v_mfma_f32_16x16x32_bf16 v[54:57], v[158:161], v[216:219], v[54:57]
	v_mfma_f32_16x16x32_bf16 v[54:57], v[162:165], v[220:223], v[54:57]
	v_mfma_f32_16x16x32_bf16 v[30:33], v[166:169], v[192:195], v[30:33]
	v_mfma_f32_16x16x32_bf16 v[30:33], v[172:175], v[196:199], v[30:33]
	v_mfma_f32_16x16x32_bf16 v[26:29], v[166:169], v[200:203], v[26:29]
	v_mfma_f32_16x16x32_bf16 v[26:29], v[172:175], v[204:207], v[26:29]
	v_mfma_f32_16x16x32_bf16 v[22:25], v[166:169], v[208:211], v[22:25]
	v_mfma_f32_16x16x32_bf16 v[22:25], v[172:175], v[212:215], v[22:25]
	v_mfma_f32_16x16x32_bf16 v[18:21], v[166:169], v[216:219], v[18:21]
	v_mfma_f32_16x16x32_bf16 v[18:21], v[172:175], v[220:223], v[18:21]
	v_mfma_f32_16x16x32_bf16 v[14:17], v[176:179], v[192:195], v[14:17]
	v_mfma_f32_16x16x32_bf16 v[14:17], v[188:191], v[196:199], v[14:17]
	v_mfma_f32_16x16x32_bf16 v[10:13], v[176:179], v[200:203], v[10:13]
	v_mfma_f32_16x16x32_bf16 v[10:13], v[188:191], v[204:207], v[10:13]
	v_mfma_f32_16x16x32_bf16 v[6:9], v[176:179], v[208:211], v[6:9]
	v_mfma_f32_16x16x32_bf16 v[6:9], v[188:191], v[212:215], v[6:9]
	v_mfma_f32_16x16x32_bf16 v[2:5], v[176:179], v[216:219], v[2:5]
	v_mfma_f32_16x16x32_bf16 v[2:5], v[188:191], v[220:223], v[2:5]
	s_barrier
	s_setprio 0
	s_add_i32 s82, s82, 2
	s_add_u32 s74, s74, 0x100
	s_addc_u32 s75, s75, 0
	s_add_u32 s80, s80, 0x100
	s_addc_u32 s81, s81, 0
	s_cmp_gt_u32 s82, 29
	s_cbranch_scc0 .LBB0_596
	s_and_b64 vcc, exec, s[62:63]
	s_cbranch_vccz .LBB0_599
	s_barrier

; #define PG8_STAGE(bufoff, gbase, voff) do { _Pragma("unroll") for (int _i = 0; _i < 2; ++_i) \
;         __builtin_amdgcn_global_load_lds((const unsigned*)((const char*)(gbase) + (voff)[_i]), (PG8_LAS unsigned*)(lds + (bufoff) + ldsw + _i * 8192), 16, 0, 0); } while (0)
; #define PG8_LDA(dst, b, h) do { _Pragma("unroll") for (int m = 0; m < 4; ++m) _Pragma("unroll") for (int k = 0; k < 2; ++k) dst[m][k] = *(const PG8_LAS bf16x8*)(lds + PG8_SA(b, h) + aoff + m * 2048 + k * 1024); } while (0)
; #define PG8_LDB(dst, b, h) do { _Pragma("unroll") for (int n = 0; n < 2; ++n) _Pragma("unroll") for (int k = 0; k < 2; ++k) dst[n][k] = *(const PG8_LAS bf16x8*)(lds + PG8_SB(b, h) + boff + n * 2048 + k * 1024); } while (0)
; #define PG8_WAIT_L(n) asm volatile("s_waitcnt lgkmcnt(" #n ")" ::: "memory")
; #define PG8_WAIT_V_SEL(sel) asm volatile("s_cmp_eq_u32 %0, 0\n\ts_cbranch_scc1 .Lw8_%=\n\ts_waitcnt vmcnt(22)\n\ts_branch .Lwd_%=\n.Lw8_%=:\n\ts_waitcnt vmcnt(8)\n.Lwd_%=:" :: "s"(sel) : "memory", "scc")
; #define PG8_BAR __builtin_amdgcn_s_barrier()
; #define PG8_SCHED __builtin_amdgcn_sched_barrier(0)
;     ...
;         for (int t = 0; t < nt * KREP; t += 2) {
;             const bool last = (t == nt * KREP - 2);
;             const int t1w = KREP > 1 ? ((t + 1) & (nt - 1)) : t + 1, t2w = KREP > 1 ? ((t + 2) & (nt - 1)) : t + 2;
;             const char* a1 = cA + (size_t)t1w * kstep;
;             const char* a2 = last ? nA : cA + (size_t)t2w * kstep; const char* b2 = last ? nB : cB + (size_t)t2w * kstep;
;             const char* a3 = a2 + kstep; const char* b3 = b2 + kstep;
;             if (last && has_next) S.a_ready(nxt);
;             const int relax = __builtin_amdgcn_readfirstlane((MK_RELAXW && t == 0 && ui > 0) ? 1 : 0);
;             if constexpr (SP2) {
;             PG8_LDB(B0, 0, 0); PG8_LDB(B1, 0, 1); PG8_SCHED; PG8_LDA(At, 0, 0); PG8_STAGE(PG8_SA(1, 1), a1 + hstep, voffA);
;             PG8_WAIT_V_SEL(relax);
;             PG8_WAIT_L(0); PG8_BAR; PG8_MMA(0, 0, At, B0); PG8_MMA(0, 1, At, B1); PG8_BAR; PG8_SCHED;
;             PG8_LDA(At, 0, 1); PG8_STAGE(PG8_SB(0, 0), b2, voffB); PG8_STAGE(PG8_SB(0, 1), b2 + hstep, voffB); PG8_STAGE(PG8_SA(0, 0), a2, voffA);
;             PG8_WAIT_V_SEL(relax);
;             PG8_WAIT_L(0); PG8_BAR; PG8_MMA(1, 0, At, B0); PG8_MMA(1, 1, At, B1); PG8_BAR; PG8_SCHED;
.LBB0_1170:
	s_add_u32 s0, s78, 0xfff80080
	s_addc_u32 s1, s79, -1
	s_add_i32 s85, 0, 0x10000
	s_cmp_eq_u32 s84, 28
	s_cselect_b32 s83, s40, s1
	s_cselect_b32 s82, s41, s0
	s_cselect_b32 s81, s67, s77
	s_cselect_b32 s80, s69, s75
	s_add_i32 s86, 0, 0x14000
	ds_read_b128 v[90:93], v184
	ds_read_b128 v[94:97], v184 offset:1024
	ds_read_b128 v[98:101], v184 offset:2048
	ds_read_b128 v[102:105], v184 offset:3072
	ds_read_b128 v[146:149], v184 offset:16384
	ds_read_b128 v[150:153], v184 offset:17408
	ds_read_b128 v[154:157], v184 offset:18432
	ds_read_b128 v[158:161], v184 offset:19456
	s_add_i32 m0, s45, 0xc000
	ds_read_b128 v[162:165], v227
	ds_read_b128 v[166:169], v227 offset:1024
	ds_read_b128 v[188:191], v227 offset:2048
	ds_read_b128 v[192:195], v227 offset:3072
	ds_read_b128 v[196:199], v227 offset:4096
	ds_read_b128 v[200:203], v227 offset:5120
	ds_read_b128 v[204:207], v227 offset:6144
	ds_read_b128 v[208:211], v227 offset:7168
	global_load_lds_dwordx4 v178, s[78:79]
	s_add_i32 m0, s45, 0xe000
	s_nop 0
	global_load_lds_dwordx4 v180, s[78:79]
	s_waitcnt vmcnt(8)
	s_waitcnt lgkmcnt(0)
	s_setprio 1
	s_barrier
	v_mfma_f32_16x16x32_bf16 v[142:145], v[90:93], v[162:165], v[142:145]
	v_mfma_f32_16x16x32_bf16 v[142:145], v[94:97], v[166:169], v[142:145]
	v_mfma_f32_16x16x32_bf16 v[126:129], v[90:93], v[188:191], v[126:129]
	v_mfma_f32_16x16x32_bf16 v[126:129], v[94:97], v[192:195], v[126:129]
	v_mfma_f32_16x16x32_bf16 v[110:113], v[90:93], v[196:199], v[110:113]
	v_mfma_f32_16x16x32_bf16 v[110:113], v[94:97], v[200:203], v[110:113]
	v_mfma_f32_16x16x32_bf16 v[78:81], v[90:93], v[204:207], v[78:81]
	v_mfma_f32_16x16x32_bf16 v[78:81], v[94:97], v[208:211], v[78:81]
	v_mfma_f32_16x16x32_bf16 v[138:141], v[98:101], v[162:165], v[138:141]
	v_mfma_f32_16x16x32_bf16 v[138:141], v[102:105], v[166:169], v[138:141]
	v_mfma_f32_16x16x32_bf16 v[122:125], v[98:101], v[188:191], v[122:125]
	v_mfma_f32_16x16x32_bf16 v[122:125], v[102:105], v[192:195], v[122:125]
	v_mfma_f32_16x16x32_bf16 v[106:109], v[98:101], v[196:199], v[106:109]
	v_mfma_f32_16x16x32_bf16 v[106:109], v[102:105], v[200:203], v[106:109]
	v_mfma_f32_16x16x32_bf16 v[74:77], v[98:101], v[204:207], v[74:77]
	v_mfma_f32_16x16x32_bf16 v[74:77], v[102:105], v[208:211], v[74:77]
	v_mfma_f32_16x16x32_bf16 v[134:137], v[146:149], v[162:165], v[134:137]
	v_mfma_f32_16x16x32_bf16 v[134:137], v[150:153], v[166:169], v[134:137]
	v_mfma_f32_16x16x32_bf16 v[118:121], v[146:149], v[188:191], v[118:121]
	v_mfma_f32_16x16x32_bf16 v[118:121], v[150:153], v[192:195], v[118:121]
	v_mfma_f32_16x16x32_bf16 v[86:89], v[146:149], v[196:199], v[86:89]
	v_mfma_f32_16x16x32_bf16 v[86:89], v[150:153], v[200:203], v[86:89]
	v_mfma_f32_16x16x32_bf16 v[70:73], v[146:149], v[204:207], v[70:73]
	v_mfma_f32_16x16x32_bf16 v[70:73], v[150:153], v[208:211], v[70:73]
	v_mfma_f32_16x16x32_bf16 v[130:133], v[154:157], v[162:165], v[130:133]
	v_mfma_f32_16x16x32_bf16 v[130:133], v[158:161], v[166:169], v[130:133]
	v_mfma_f32_16x16x32_bf16 v[114:117], v[154:157], v[188:191], v[114:117]
	v_mfma_f32_16x16x32_bf16 v[114:117], v[158:161], v[192:195], v[114:117]
	v_mfma_f32_16x16x32_bf16 v[82:85], v[154:157], v[196:199], v[82:85]
	v_mfma_f32_16x16x32_bf16 v[82:85], v[158:161], v[200:203], v[82:85]
	v_mfma_f32_16x16x32_bf16 v[66:69], v[154:157], v[204:207], v[66:69]
	v_mfma_f32_16x16x32_bf16 v[66:69], v[158:161], v[208:211], v[66:69]
	s_barrier
	s_setprio 0
	s_add_i32 s0, s85, s33
	s_mov_b32 m0, s0
	ds_read_b128 v[162:165], v227 offset:16384
	ds_read_b128 v[166:169], v227 offset:17408
	ds_read_b128 v[188:191], v227 offset:18432
	ds_read_b128 v[192:195], v227 offset:19456
	ds_read_b128 v[196:199], v227 offset:20480
	ds_read_b128 v[200:203], v227 offset:21504
	ds_read_b128 v[204:207], v227 offset:22528
	ds_read_b128 v[208:211], v227 offset:23552
	global_load_lds_dwordx4 v182, s[80:81]
	s_add_i32 m0, s0, 0x2000
	s_add_u32 s0, s80, 0x80000
	s_addc_u32 s1, s81, 0
	s_add_i32 s85, s86, s33
	global_load_lds_dwordx4 v176, s[80:81]
	s_mov_b32 m0, s85
	s_nop 0
	global_load_lds_dwordx4 v182, s[0:1]
	s_add_i32 m0, s85, 0x2000
	s_nop 0
	global_load_lds_dwordx4 v176, s[0:1]
	s_mov_b32 m0, s45
	s_nop 0
	global_load_lds_dwordx4 v172, s[82:83]
	s_mov_b32 m0, s46
	s_nop 0
	global_load_lds_dwordx4 v174, s[82:83]
	s_waitcnt vmcnt(8)
	s_waitcnt lgkmcnt(0)
	s_setprio 1
	s_barrier
	v_mfma_f32_16x16x32_bf16 v[62:65], v[90:93], v[162:165], v[62:65]
	v_mfma_f32_16x16x32_bf16 v[62:65], v[94:97], v[166:169], v[62:65]
	v_mfma_f32_16x16x32_bf16 v[46:49], v[90:93], v[188:191], v[46:49]
	v_mfma_f32_16x16x32_bf16 v[46:49], v[94:97], v[192:195], v[46:49]
	v_mfma_f32_16x16x32_bf16 v[30:33], v[90:93], v[196:199], v[30:33]
	v_mfma_f32_16x16x32_bf16 v[30:33], v[94:97], v[200:203], v[30:33]
	v_mfma_f32_16x16x32_bf16 v[14:17], v[90:93], v[204:207], v[14:17]
	v_mfma_f32_16x16x32_bf16 v[14:17], v[94:97], v[208:211], v[14:17]
	v_mfma_f32_16x16x32_bf16 v[58:61], v[98:101], v[162:165], v[58:61]
	v_mfma_f32_16x16x32_bf16 v[58:61], v[102:105], v[166:169], v[58:61]
	v_mfma_f32_16x16x32_bf16 v[42:45], v[98:101], v[188:191], v[42:45]
	v_mfma_f32_16x16x32_bf16 v[42:45], v[102:105], v[192:195], v[42:45]
	v_mfma_f32_16x16x32_bf16 v[26:29], v[98:101], v[196:199], v[26:29]
	v_mfma_f32_16x16x32_bf16 v[26:29], v[102:105], v[200:203], v[26:29]
	v_mfma_f32_16x16x32_bf16 v[10:13], v[98:101], v[204:207], v[10:13]
	v_mfma_f32_16x16x32_bf16 v[10:13], v[102:105], v[208:211], v[10:13]
	v_mfma_f32_16x16x32_bf16 v[54:57], v[146:149], v[162:165], v[54:57]
	v_mfma_f32_16x16x32_bf16 v[54:57], v[150:153], v[166:169], v[54:57]
	v_mfma_f32_16x16x32_bf16 v[38:41], v[146:149], v[188:191], v[38:41]
	v_mfma_f32_16x16x32_bf16 v[38:41], v[150:153], v[192:195], v[38:41]
	v_mfma_f32_16x16x32_bf16 v[22:25], v[146:149], v[196:199], v[22:25]
	v_mfma_f32_16x16x32_bf16 v[22:25], v[150:153], v[200:203], v[22:25]
	v_mfma_f32_16x16x32_bf16 v[6:9], v[146:149], v[204:207], v[6:9]
	v_mfma_f32_16x16x32_bf16 v[6:9], v[150:153], v[208:211], v[6:9]
	v_mfma_f32_16x16x32_bf16 v[50:53], v[154:157], v[162:165], v[50:53]
	v_mfma_f32_16x16x32_bf16 v[50:53], v[158:161], v[166:169], v[50:53]
	v_mfma_f32_16x16x32_bf16 v[34:37], v[154:157], v[188:191], v[34:37]
	v_mfma_f32_16x16x32_bf16 v[34:37], v[158:161], v[192:195], v[34:37]
	v_mfma_f32_16x16x32_bf16 v[18:21], v[154:157], v[196:199], v[18:21]
	v_mfma_f32_16x16x32_bf16 v[18:21], v[158:161], v[200:203], v[18:21]
	v_mfma_f32_16x16x32_bf16 v[2:5], v[154:157], v[204:207], v[2:5]
	v_mfma_f32_16x16x32_bf16 v[2:5], v[158:161], v[208:211], v[2:5]
	s_barrier
; #define PG8_STAGE(bufoff, gbase, voff) do { _Pragma("unroll") for (int _i = 0; _i < 2; ++_i) \
;         __builtin_amdgcn_global_load_lds((const unsigned*)((const char*)(gbase) + (voff)[_i]), (PG8_LAS unsigned*)(lds + (bufoff) + ldsw + _i * 8192), 16, 0, 0); } while (0)
; #define PG8_LDA(dst, b, h) do { _Pragma("unroll") for (int m = 0; m < 4; ++m) _Pragma("unroll") for (int k = 0; k < 2; ++k) dst[m][k] = *(const PG8_LAS bf16x8*)(lds + PG8_SA(b, h) + aoff + m * 2048 + k * 1024); } while (0)
; #define PG8_LDB(dst, b, h) do { _Pragma("unroll") for (int n = 0; n < 2; ++n) _Pragma("unroll") for (int k = 0; k < 2; ++k) dst[n][k] = *(const PG8_LAS bf16x8*)(lds + PG8_SB(b, h) + boff + n * 2048 + k * 1024); } while (0)
; #define PG8_WAIT_V(n) asm volatile("s_waitcnt vmcnt(" #n ")" ::: "memory")
; #define PG8_WAIT_L(n) asm volatile("s_waitcnt lgkmcnt(" #n ")" ::: "memory")
; #define PG8_WAIT_V_SEL(sel) asm volatile("s_cmp_eq_u32 %0, 0\n\ts_cbranch_scc1 .Lw8_%=\n\ts_waitcnt vmcnt(22)\n\ts_branch .Lwd_%=\n.Lw8_%=:\n\ts_waitcnt vmcnt(8)\n.Lwd_%=:" :: "s"(sel) : "memory", "scc")
; #define PG8_BAR __builtin_amdgcn_s_barrier()
; #define PG8_SCHED __builtin_amdgcn_sched_barrier(0)
;     ...
;             PG8_LDB(B0, 0, 0); PG8_LDB(B1, 0, 1); PG8_SCHED; PG8_LDA(At, 0, 0); PG8_STAGE(PG8_SA(1, 1), a1 + hstep, voffA);
;             PG8_WAIT_V_SEL(relax);
;             PG8_WAIT_L(0); PG8_BAR; PG8_MMA(0, 0, At, B0); PG8_MMA(0, 1, At, B1); PG8_BAR; PG8_SCHED;
;             PG8_LDA(At, 0, 1); PG8_STAGE(PG8_SB(0, 0), b2, voffB); PG8_STAGE(PG8_SB(0, 1), b2 + hstep, voffB); PG8_STAGE(PG8_SA(0, 0), a2, voffA);
;             PG8_WAIT_V_SEL(relax);
;             PG8_WAIT_L(0); PG8_BAR; PG8_MMA(1, 0, At, B0); PG8_MMA(1, 1, At, B1); PG8_BAR; PG8_SCHED;
;             PG8_LDB(B0, 1, 0); PG8_LDB(B1, 1, 1); PG8_SCHED; PG8_LDA(At, 1, 0); PG8_STAGE(PG8_SA(0, 1), a2 + hstep, voffA);
;             PG8_WAIT_V(8); PG8_WAIT_L(0); PG8_BAR; PG8_MMA(0, 0, At, B0); PG8_MMA(0, 1, At, B1); PG8_BAR; PG8_SCHED;
;             PG8_LDA(At, 1, 1); PG8_STAGE(PG8_SB(1, 0), b3, voffB); PG8_STAGE(PG8_SB(1, 1), b3 + hstep, voffB); PG8_STAGE(PG8_SA(1, 0), a3, voffA);
;             PG8_WAIT_V(8); PG8_WAIT_L(0); PG8_BAR; PG8_MMA(1, 0, At, B0); PG8_MMA(1, 1, At, B1); PG8_BAR; PG8_SCHED;
	s_setprio 0
	s_add_i32 s85, 0, 0x18000
	s_add_i32 s86, 0, 0x1c000
	ds_read_b128 v[90:93], v184 offset:32768
	ds_read_b128 v[94:97], v184 offset:33792
	ds_read_b128 v[98:101], v184 offset:34816
	ds_read_b128 v[102:105], v184 offset:35840
	ds_read_b128 v[146:149], v184 offset:49152
	ds_read_b128 v[150:153], v184 offset:50176
	ds_read_b128 v[154:157], v184 offset:51200
	ds_read_b128 v[158:161], v184 offset:52224
	s_add_u32 s0, s82, 0x80000
	s_addc_u32 s1, s83, 0
	s_mov_b32 m0, s47
	ds_read_b128 v[162:165], v227 offset:32768
	ds_read_b128 v[166:169], v227 offset:33792
	ds_read_b128 v[188:191], v227 offset:34816
	ds_read_b128 v[192:195], v227 offset:35840
	ds_read_b128 v[196:199], v227 offset:36864
	ds_read_b128 v[200:203], v227 offset:37888
	ds_read_b128 v[204:207], v227 offset:38912
	ds_read_b128 v[208:211], v227 offset:39936
	global_load_lds_dwordx4 v172, s[0:1]
	s_mov_b32 m0, s48
	s_nop 0
	global_load_lds_dwordx4 v174, s[0:1]
	s_waitcnt vmcnt(8)
	s_waitcnt lgkmcnt(0)
	s_setprio 1
	s_barrier
	v_mfma_f32_16x16x32_bf16 v[142:145], v[90:93], v[162:165], v[142:145]
	v_mfma_f32_16x16x32_bf16 v[142:145], v[94:97], v[166:169], v[142:145]
	v_mfma_f32_16x16x32_bf16 v[126:129], v[90:93], v[188:191], v[126:129]
	v_mfma_f32_16x16x32_bf16 v[126:129], v[94:97], v[192:195], v[126:129]
	v_mfma_f32_16x16x32_bf16 v[110:113], v[90:93], v[196:199], v[110:113]
	v_mfma_f32_16x16x32_bf16 v[110:113], v[94:97], v[200:203], v[110:113]
	v_mfma_f32_16x16x32_bf16 v[78:81], v[90:93], v[204:207], v[78:81]
	v_mfma_f32_16x16x32_bf16 v[78:81], v[94:97], v[208:211], v[78:81]
	v_mfma_f32_16x16x32_bf16 v[138:141], v[98:101], v[162:165], v[138:141]
	v_mfma_f32_16x16x32_bf16 v[138:141], v[102:105], v[166:169], v[138:141]
	v_mfma_f32_16x16x32_bf16 v[122:125], v[98:101], v[188:191], v[122:125]
	v_mfma_f32_16x16x32_bf16 v[122:125], v[102:105], v[192:195], v[122:125]
	v_mfma_f32_16x16x32_bf16 v[106:109], v[98:101], v[196:199], v[106:109]
	v_mfma_f32_16x16x32_bf16 v[106:109], v[102:105], v[200:203], v[106:109]
	v_mfma_f32_16x16x32_bf16 v[74:77], v[98:101], v[204:207], v[74:77]
	v_mfma_f32_16x16x32_bf16 v[74:77], v[102:105], v[208:211], v[74:77]
	v_mfma_f32_16x16x32_bf16 v[134:137], v[146:149], v[162:165], v[134:137]
	v_mfma_f32_16x16x32_bf16 v[134:137], v[150:153], v[166:169], v[134:137]
	v_mfma_f32_16x16x32_bf16 v[118:121], v[146:149], v[188:191], v[118:121]
	v_mfma_f32_16x16x32_bf16 v[118:121], v[150:153], v[192:195], v[118:121]
	v_mfma_f32_16x16x32_bf16 v[86:89], v[146:149], v[196:199], v[86:89]
	v_mfma_f32_16x16x32_bf16 v[86:89], v[150:153], v[200:203], v[86:89]
	v_mfma_f32_16x16x32_bf16 v[70:73], v[146:149], v[204:207], v[70:73]
	v_mfma_f32_16x16x32_bf16 v[70:73], v[150:153], v[208:211], v[70:73]
	v_mfma_f32_16x16x32_bf16 v[130:133], v[154:157], v[162:165], v[130:133]
	v_mfma_f32_16x16x32_bf16 v[130:133], v[158:161], v[166:169], v[130:133]
	v_mfma_f32_16x16x32_bf16 v[114:117], v[154:157], v[188:191], v[114:117]
	v_mfma_f32_16x16x32_bf16 v[114:117], v[158:161], v[192:195], v[114:117]
	v_mfma_f32_16x16x32_bf16 v[82:85], v[154:157], v[196:199], v[82:85]
	v_mfma_f32_16x16x32_bf16 v[82:85], v[158:161], v[200:203], v[82:85]
	v_mfma_f32_16x16x32_bf16 v[66:69], v[154:157], v[204:207], v[66:69]
	v_mfma_f32_16x16x32_bf16 v[66:69], v[158:161], v[208:211], v[66:69]
	s_barrier
	s_setprio 0
	s_add_i32 s0, s85, s33
	s_mov_b32 m0, s0
	ds_read_b128 v[162:165], v227 offset:49152
	ds_read_b128 v[166:169], v227 offset:50176
	ds_read_b128 v[188:191], v227 offset:51200
	ds_read_b128 v[192:195], v227 offset:52224
	ds_read_b128 v[196:199], v227 offset:53248
	ds_read_b128 v[200:203], v227 offset:54272
	ds_read_b128 v[204:207], v227 offset:55296
	ds_read_b128 v[208:211], v227 offset:56320
	s_add_u32 s100, s80, 0x80
	s_addc_u32 s101, s81, 0
	global_load_lds_dwordx4 v182, s[100:101]
	s_add_i32 m0, s0, 0x2000
	s_add_u32 s0, s80, 0x80080
	s_addc_u32 s1, s81, 0
	s_add_i32 s80, s86, s33
	global_load_lds_dwordx4 v176, s[100:101]
	s_mov_b32 m0, s80
	s_nop 0
	global_load_lds_dwordx4 v182, s[0:1]
	s_add_i32 m0, s80, 0x2000
	s_nop 0
	global_load_lds_dwordx4 v176, s[0:1]
	s_mov_b32 m0, s50
	s_nop 0
	s_add_u32 s100, s82, 0x80
	s_addc_u32 s101, s83, 0
	global_load_lds_dwordx4 v172, s[100:101]
	s_mov_b32 m0, s51
	s_nop 0
	global_load_lds_dwordx4 v174, s[100:101]
	s_waitcnt vmcnt(8)
	s_waitcnt lgkmcnt(0)
	s_setprio 1
	s_barrier
	v_mfma_f32_16x16x32_bf16 v[62:65], v[90:93], v[162:165], v[62:65]
	v_mfma_f32_16x16x32_bf16 v[62:65], v[94:97], v[166:169], v[62:65]
	v_mfma_f32_16x16x32_bf16 v[46:49], v[90:93], v[188:191], v[46:49]
	v_mfma_f32_16x16x32_bf16 v[46:49], v[94:97], v[192:195], v[46:49]
	v_mfma_f32_16x16x32_bf16 v[30:33], v[90:93], v[196:199], v[30:33]
	v_mfma_f32_16x16x32_bf16 v[30:33], v[94:97], v[200:203], v[30:33]
	v_mfma_f32_16x16x32_bf16 v[14:17], v[90:93], v[204:207], v[14:17]
	v_mfma_f32_16x16x32_bf16 v[14:17], v[94:97], v[208:211], v[14:17]
	v_mfma_f32_16x16x32_bf16 v[58:61], v[98:101], v[162:165], v[58:61]
	v_mfma_f32_16x16x32_bf16 v[58:61], v[102:105], v[166:169], v[58:61]
	v_mfma_f32_16x16x32_bf16 v[42:45], v[98:101], v[188:191], v[42:45]
	v_mfma_f32_16x16x32_bf16 v[42:45], v[102:105], v[192:195], v[42:45]
	v_mfma_f32_16x16x32_bf16 v[26:29], v[98:101], v[196:199], v[26:29]
	v_mfma_f32_16x16x32_bf16 v[26:29], v[102:105], v[200:203], v[26:29]
	v_mfma_f32_16x16x32_bf16 v[10:13], v[98:101], v[204:207], v[10:13]
	v_mfma_f32_16x16x32_bf16 v[10:13], v[102:105], v[208:211], v[10:13]
	v_mfma_f32_16x16x32_bf16 v[54:57], v[146:149], v[162:165], v[54:57]
	v_mfma_f32_16x16x32_bf16 v[54:57], v[150:153], v[166:169], v[54:57]
	v_mfma_f32_16x16x32_bf16 v[38:41], v[146:149], v[188:191], v[38:41]
	v_mfma_f32_16x16x32_bf16 v[38:41], v[150:153], v[192:195], v[38:41]
	v_mfma_f32_16x16x32_bf16 v[22:25], v[146:149], v[196:199], v[22:25]
	v_mfma_f32_16x16x32_bf16 v[22:25], v[150:153], v[200:203], v[22:25]
	v_mfma_f32_16x16x32_bf16 v[6:9], v[146:149], v[204:207], v[6:9]
	v_mfma_f32_16x16x32_bf16 v[6:9], v[150:153], v[208:211], v[6:9]
	v_mfma_f32_16x16x32_bf16 v[50:53], v[154:157], v[162:165], v[50:53]
	v_mfma_f32_16x16x32_bf16 v[50:53], v[158:161], v[166:169], v[50:53]
	v_mfma_f32_16x16x32_bf16 v[34:37], v[154:157], v[188:191], v[34:37]
	v_mfma_f32_16x16x32_bf16 v[34:37], v[158:161], v[192:195], v[34:37]
	v_mfma_f32_16x16x32_bf16 v[18:21], v[154:157], v[196:199], v[18:21]
	v_mfma_f32_16x16x32_bf16 v[18:21], v[158:161], v[200:203], v[18:21]
	v_mfma_f32_16x16x32_bf16 v[2:5], v[154:157], v[204:207], v[2:5]
	v_mfma_f32_16x16x32_bf16 v[2:5], v[158:161], v[208:211], v[2:5]
	s_barrier
	s_setprio 0
	s_add_i32 s84, s84, 2
	s_add_u32 s78, s78, 0x100
	s_addc_u32 s79, s79, 0
	s_add_u32 s75, s75, 0x100
	s_addc_u32 s77, s77, 0
	s_cmp_gt_u32 s84, 29
	s_cbranch_scc0 .LBB0_1170
	s_and_b64 vcc, exec, s[64:65]
	s_cbranch_vccz .LBB0_1173
	s_barrier

; #define PG8_STAGE(bufoff, gbase, voff) do { _Pragma("unroll") for (int _i = 0; _i < 2; ++_i) \
;         __builtin_amdgcn_global_load_lds((const unsigned*)((const char*)(gbase) + (voff)[_i]), (PG8_LAS unsigned*)(lds + (bufoff) + ldsw + _i * 8192), 16, 0, 0); } while (0)
; #define PG8_LDA(dst, b, h) do { _Pragma("unroll") for (int m = 0; m < 4; ++m) _Pragma("unroll") for (int k = 0; k < 2; ++k) dst[m][k] = *(const PG8_LAS bf16x8*)(lds + PG8_SA(b, h) + aoff + m * 2048 + k * 1024); } while (0)
; #define PG8_LDB(dst, b, h) do { _Pragma("unroll") for (int n = 0; n < 2; ++n) _Pragma("unroll") for (int k = 0; k < 2; ++k) dst[n][k] = *(const PG8_LAS bf16x8*)(lds + PG8_SB(b, h) + boff + n * 2048 + k * 1024); } while (0)
; #define PG8_WAIT_L(n) asm volatile("s_waitcnt lgkmcnt(" #n ")" ::: "memory")
; #define PG8_WAIT_V_SEL(sel) asm volatile("s_cmp_eq_u32 %0, 0\n\ts_cbranch_scc1 .Lw8_%=\n\ts_waitcnt vmcnt(22)\n\ts_branch .Lwd_%=\n.Lw8_%=:\n\ts_waitcnt vmcnt(8)\n.Lwd_%=:" :: "s"(sel) : "memory", "scc")
; #define PG8_BAR __builtin_amdgcn_s_barrier()
; #define PG8_SCHED __builtin_amdgcn_sched_barrier(0)
;     ...
;         for (int t = 0; t < nt * KREP; t += 2) {
;             const bool last = (t == nt * KREP - 2);
;             const int t1w = KREP > 1 ? ((t + 1) & (nt - 1)) : t + 1, t2w = KREP > 1 ? ((t + 2) & (nt - 1)) : t + 2;
;             const char* a1 = cA + (size_t)t1w * kstep;
;             const char* a2 = last ? nA : cA + (size_t)t2w * kstep; const char* b2 = last ? nB : cB + (size_t)t2w * kstep;
;             const char* a3 = a2 + kstep; const char* b3 = b2 + kstep;
;             if (last && has_next) S.a_ready(nxt);
;             const int relax = __builtin_amdgcn_readfirstlane((MK_RELAXW && t == 0 && ui > 0) ? 1 : 0);
;             if constexpr (SP2) {
;             PG8_LDB(B0, 0, 0); PG8_LDB(B1, 0, 1); PG8_SCHED; PG8_LDA(At, 0, 0); PG8_STAGE(PG8_SA(1, 1), a1 + hstep, voffA);
;             PG8_WAIT_V_SEL(relax);
;             PG8_WAIT_L(0); PG8_BAR; PG8_MMA(0, 0, At, B0); PG8_MMA(0, 1, At, B1); PG8_BAR; PG8_SCHED;
;             PG8_LDA(At, 0, 1); PG8_STAGE(PG8_SB(0, 0), b2, voffB); PG8_STAGE(PG8_SB(0, 1), b2 + hstep, voffB); PG8_STAGE(PG8_SA(0, 0), a2, voffA);
;             PG8_WAIT_V_SEL(relax);
;             PG8_WAIT_L(0); PG8_BAR; PG8_MMA(1, 0, At, B0); PG8_MMA(1, 1, At, B1); PG8_BAR; PG8_SCHED;
.LBB0_1327:
	s_add_u32 s96, s12, 0x100
	s_addc_u32 s97, s13, 0
	s_add_i32 s51, 0, 0x10000
	s_cmp_eq_u32 s0, 28
	s_cselect_b32 s41, s59, s97
	s_cselect_b32 s40, s64, s96
	s_cselect_b32 vcc_hi, s65, s67
	s_cselect_b32 vcc_lo, s87, s66
	s_add_i32 s19, 0, 0x14000
	ds_read_b128 v[66:69], v200
	ds_read_b128 v[70:73], v200 offset:1024
	ds_read_b128 v[82:85], v200 offset:2048
	ds_read_b128 v[142:145], v200 offset:3072
	ds_read_b128 v[146:149], v200 offset:16384
	ds_read_b128 v[150:153], v200 offset:17408
	ds_read_b128 v[154:157], v200 offset:18432
	ds_read_b128 v[158:161], v200 offset:19456
	s_add_i32 m0, s95, 0xc000
	ds_read_b128 v[162:165], v219
	ds_read_b128 v[166:169], v219 offset:1024
	ds_read_b128 v[170:173], v219 offset:2048
	ds_read_b128 v[174:177], v219 offset:3072
	ds_read_b128 v[178:181], v219 offset:4096
	ds_read_b128 v[184:187], v219 offset:5120
	ds_read_b128 v[220:223], v219 offset:6144
	ds_read_b128 v[224:227], v219 offset:7168
	global_load_lds_dwordx4 v196, s[12:13]
	s_add_i32 m0, s95, 0xe000
	s_nop 0
	global_load_lds_dwordx4 v198, s[12:13]
	s_waitcnt vmcnt(8)
	s_waitcnt lgkmcnt(0)
	s_setprio 1
	s_barrier
	v_mfma_f32_16x16x32_bf16 v[114:117], v[66:69], v[162:165], v[114:117]
	v_mfma_f32_16x16x32_bf16 v[114:117], v[70:73], v[166:169], v[114:117]
	v_mfma_f32_16x16x32_bf16 v[110:113], v[66:69], v[170:173], v[110:113]
	v_mfma_f32_16x16x32_bf16 v[110:113], v[70:73], v[174:177], v[110:113]
	v_mfma_f32_16x16x32_bf16 v[78:81], v[66:69], v[178:181], v[78:81]
	v_mfma_f32_16x16x32_bf16 v[78:81], v[70:73], v[184:187], v[78:81]
	v_mfma_f32_16x16x32_bf16 v[74:77], v[66:69], v[220:223], v[74:77]
	v_mfma_f32_16x16x32_bf16 v[74:77], v[70:73], v[224:227], v[74:77]
	v_mfma_f32_16x16x32_bf16 v[106:109], v[82:85], v[162:165], v[106:109]
	v_mfma_f32_16x16x32_bf16 v[106:109], v[142:145], v[166:169], v[106:109]
	v_mfma_f32_16x16x32_bf16 v[102:105], v[82:85], v[170:173], v[102:105]
	v_mfma_f32_16x16x32_bf16 v[102:105], v[142:145], v[174:177], v[102:105]
	v_mfma_f32_16x16x32_bf16 v[138:141], v[82:85], v[178:181], v[138:141]
	v_mfma_f32_16x16x32_bf16 v[138:141], v[142:145], v[184:187], v[138:141]
	v_mfma_f32_16x16x32_bf16 v[134:137], v[82:85], v[220:223], v[134:137]
	v_mfma_f32_16x16x32_bf16 v[134:137], v[142:145], v[224:227], v[134:137]
	v_mfma_f32_16x16x32_bf16 v[98:101], v[146:149], v[162:165], v[98:101]
	v_mfma_f32_16x16x32_bf16 v[98:101], v[150:153], v[166:169], v[98:101]
	v_mfma_f32_16x16x32_bf16 v[94:97], v[146:149], v[170:173], v[94:97]
	v_mfma_f32_16x16x32_bf16 v[94:97], v[150:153], v[174:177], v[94:97]
	v_mfma_f32_16x16x32_bf16 v[130:133], v[146:149], v[178:181], v[130:133]
	v_mfma_f32_16x16x32_bf16 v[130:133], v[150:153], v[184:187], v[130:133]
	v_mfma_f32_16x16x32_bf16 v[126:129], v[146:149], v[220:223], v[126:129]
	v_mfma_f32_16x16x32_bf16 v[126:129], v[150:153], v[224:227], v[126:129]
	v_mfma_f32_16x16x32_bf16 v[90:93], v[154:157], v[162:165], v[90:93]
	v_mfma_f32_16x16x32_bf16 v[90:93], v[158:161], v[166:169], v[90:93]
	v_mfma_f32_16x16x32_bf16 v[86:89], v[154:157], v[170:173], v[86:89]
	v_mfma_f32_16x16x32_bf16 v[86:89], v[158:161], v[174:177], v[86:89]
	v_mfma_f32_16x16x32_bf16 v[122:125], v[154:157], v[178:181], v[122:125]
	v_mfma_f32_16x16x32_bf16 v[122:125], v[158:161], v[184:187], v[122:125]
	v_mfma_f32_16x16x32_bf16 v[118:121], v[154:157], v[220:223], v[118:121]
	v_mfma_f32_16x16x32_bf16 v[118:121], v[158:161], v[224:227], v[118:121]
	s_barrier
	s_setprio 0
	s_add_i32 s12, s51, s37
	s_mov_b32 m0, s12
	ds_read_b128 v[162:165], v219 offset:16384
	ds_read_b128 v[166:169], v219 offset:17408
	ds_read_b128 v[170:173], v219 offset:18432
	ds_read_b128 v[174:177], v219 offset:19456
	ds_read_b128 v[178:181], v219 offset:20480
	ds_read_b128 v[184:187], v219 offset:21504
	ds_read_b128 v[220:223], v219 offset:22528
	ds_read_b128 v[224:227], v219 offset:23552
	global_load_lds_dwordx4 v182, vcc
	s_add_i32 m0, s12, 0x2000
	s_add_u32 s12, vcc_lo, 0x80000
	s_addc_u32 s13, vcc_hi, 0
	s_add_i32 s19, s19, s37
	global_load_lds_dwordx4 v192, vcc
	s_mov_b32 m0, s19
	s_nop 0
	global_load_lds_dwordx4 v182, s[12:13]
	s_add_i32 m0, s19, 0x2000
	s_nop 0
	global_load_lds_dwordx4 v192, s[12:13]
	s_mov_b32 m0, s95
	s_nop 0
	global_load_lds_dwordx4 v188, s[40:41]
	s_mov_b32 m0, s20
	s_nop 0
	global_load_lds_dwordx4 v190, s[40:41]
	s_waitcnt vmcnt(8)
	s_waitcnt lgkmcnt(0)
	s_setprio 1
	s_barrier
	v_mfma_f32_16x16x32_bf16 v[30:33], v[66:69], v[162:165], v[30:33]
	v_mfma_f32_16x16x32_bf16 v[30:33], v[70:73], v[166:169], v[30:33]
	v_mfma_f32_16x16x32_bf16 v[26:29], v[66:69], v[170:173], v[26:29]
	v_mfma_f32_16x16x32_bf16 v[26:29], v[70:73], v[174:177], v[26:29]
	v_mfma_f32_16x16x32_bf16 v[62:65], v[66:69], v[178:181], v[62:65]
	v_mfma_f32_16x16x32_bf16 v[62:65], v[70:73], v[184:187], v[62:65]
	v_mfma_f32_16x16x32_bf16 v[58:61], v[66:69], v[220:223], v[58:61]
	v_mfma_f32_16x16x32_bf16 v[58:61], v[70:73], v[224:227], v[58:61]
	v_mfma_f32_16x16x32_bf16 v[22:25], v[82:85], v[162:165], v[22:25]
	v_mfma_f32_16x16x32_bf16 v[22:25], v[142:145], v[166:169], v[22:25]
	v_mfma_f32_16x16x32_bf16 v[18:21], v[82:85], v[170:173], v[18:21]
	v_mfma_f32_16x16x32_bf16 v[18:21], v[142:145], v[174:177], v[18:21]
	v_mfma_f32_16x16x32_bf16 v[54:57], v[82:85], v[178:181], v[54:57]
	v_mfma_f32_16x16x32_bf16 v[54:57], v[142:145], v[184:187], v[54:57]
	v_mfma_f32_16x16x32_bf16 v[50:53], v[82:85], v[220:223], v[50:53]
	v_mfma_f32_16x16x32_bf16 v[50:53], v[142:145], v[224:227], v[50:53]
	v_mfma_f32_16x16x32_bf16 v[14:17], v[146:149], v[162:165], v[14:17]
	v_mfma_f32_16x16x32_bf16 v[14:17], v[150:153], v[166:169], v[14:17]
	v_mfma_f32_16x16x32_bf16 v[10:13], v[146:149], v[170:173], v[10:13]
	v_mfma_f32_16x16x32_bf16 v[10:13], v[150:153], v[174:177], v[10:13]
	v_mfma_f32_16x16x32_bf16 v[46:49], v[146:149], v[178:181], v[46:49]
	v_mfma_f32_16x16x32_bf16 v[46:49], v[150:153], v[184:187], v[46:49]
	v_mfma_f32_16x16x32_bf16 v[38:41], v[146:149], v[220:223], v[38:41]
	v_mfma_f32_16x16x32_bf16 v[38:41], v[150:153], v[224:227], v[38:41]
	v_mfma_f32_16x16x32_bf16 v[6:9], v[154:157], v[162:165], v[6:9]
	v_mfma_f32_16x16x32_bf16 v[6:9], v[158:161], v[166:169], v[6:9]
	v_mfma_f32_16x16x32_bf16 v[2:5], v[154:157], v[170:173], v[2:5]
	v_mfma_f32_16x16x32_bf16 v[2:5], v[158:161], v[174:177], v[2:5]
	v_mfma_f32_16x16x32_bf16 v[34:37], v[154:157], v[178:181], v[34:37]
	v_mfma_f32_16x16x32_bf16 v[34:37], v[158:161], v[184:187], v[34:37]
	v_mfma_f32_16x16x32_bf16 v[42:45], v[154:157], v[220:223], v[42:45]
	v_mfma_f32_16x16x32_bf16 v[42:45], v[158:161], v[224:227], v[42:45]
	s_barrier
; #define PG8_STAGE(bufoff, gbase, voff) do { _Pragma("unroll") for (int _i = 0; _i < 2; ++_i) \
;         __builtin_amdgcn_global_load_lds((const unsigned*)((const char*)(gbase) + (voff)[_i]), (PG8_LAS unsigned*)(lds + (bufoff) + ldsw + _i * 8192), 16, 0, 0); } while (0)
; #define PG8_LDA(dst, b, h) do { _Pragma("unroll") for (int m = 0; m < 4; ++m) _Pragma("unroll") for (int k = 0; k < 2; ++k) dst[m][k] = *(const PG8_LAS bf16x8*)(lds + PG8_SA(b, h) + aoff + m * 2048 + k * 1024); } while (0)
; #define PG8_LDB(dst, b, h) do { _Pragma("unroll") for (int n = 0; n < 2; ++n) _Pragma("unroll") for (int k = 0; k < 2; ++k) dst[n][k] = *(const PG8_LAS bf16x8*)(lds + PG8_SB(b, h) + boff + n * 2048 + k * 1024); } while (0)
; #define PG8_WAIT_V(n) asm volatile("s_waitcnt vmcnt(" #n ")" ::: "memory")
; #define PG8_WAIT_L(n) asm volatile("s_waitcnt lgkmcnt(" #n ")" ::: "memory")
; #define PG8_WAIT_V_SEL(sel) asm volatile("s_cmp_eq_u32 %0, 0\n\ts_cbranch_scc1 .Lw8_%=\n\ts_waitcnt vmcnt(22)\n\ts_branch .Lwd_%=\n.Lw8_%=:\n\ts_waitcnt vmcnt(8)\n.Lwd_%=:" :: "s"(sel) : "memory", "scc")
; #define PG8_BAR __builtin_amdgcn_s_barrier()
; #define PG8_SCHED __builtin_amdgcn_sched_barrier(0)
;     ...
;             PG8_LDB(B0, 0, 0); PG8_LDB(B1, 0, 1); PG8_SCHED; PG8_LDA(At, 0, 0); PG8_STAGE(PG8_SA(1, 1), a1 + hstep, voffA);
;             PG8_WAIT_V_SEL(relax);
;             PG8_WAIT_L(0); PG8_BAR; PG8_MMA(0, 0, At, B0); PG8_MMA(0, 1, At, B1); PG8_BAR; PG8_SCHED;
;             PG8_LDA(At, 0, 1); PG8_STAGE(PG8_SB(0, 0), b2, voffB); PG8_STAGE(PG8_SB(0, 1), b2 + hstep, voffB); PG8_STAGE(PG8_SA(0, 0), a2, voffA);
;             PG8_WAIT_V_SEL(relax);
;             PG8_WAIT_L(0); PG8_BAR; PG8_MMA(1, 0, At, B0); PG8_MMA(1, 1, At, B1); PG8_BAR; PG8_SCHED;
;             PG8_LDB(B0, 1, 0); PG8_LDB(B1, 1, 1); PG8_SCHED; PG8_LDA(At, 1, 0); PG8_STAGE(PG8_SA(0, 1), a2 + hstep, voffA);
;             PG8_WAIT_V(8); PG8_WAIT_L(0); PG8_BAR; PG8_MMA(0, 0, At, B0); PG8_MMA(0, 1, At, B1); PG8_BAR; PG8_SCHED;
;             PG8_LDA(At, 1, 1); PG8_STAGE(PG8_SB(1, 0), b3, voffB); PG8_STAGE(PG8_SB(1, 1), b3 + hstep, voffB); PG8_STAGE(PG8_SA(1, 0), a3, voffA);
;             PG8_WAIT_V(8); PG8_WAIT_L(0); PG8_BAR; PG8_MMA(1, 0, At, B0); PG8_MMA(1, 1, At, B1); PG8_BAR; PG8_SCHED;
	s_setprio 0
	s_add_i32 s19, 0, 0x18000
	s_add_i32 s51, 0, 0x1c000
	ds_read_b128 v[66:69], v200 offset:32768
	ds_read_b128 v[70:73], v200 offset:33792
	ds_read_b128 v[82:85], v200 offset:34816
	ds_read_b128 v[142:145], v200 offset:35840
	ds_read_b128 v[146:149], v200 offset:49152
	ds_read_b128 v[150:153], v200 offset:50176
	ds_read_b128 v[154:157], v200 offset:51200
	ds_read_b128 v[158:161], v200 offset:52224
	s_add_u32 s12, s40, 0x80000
	s_addc_u32 s13, s41, 0
	s_mov_b32 m0, s44
	ds_read_b128 v[162:165], v219 offset:32768
	ds_read_b128 v[166:169], v219 offset:33792
	ds_read_b128 v[170:173], v219 offset:34816
	ds_read_b128 v[174:177], v219 offset:35840
	ds_read_b128 v[178:181], v219 offset:36864
	ds_read_b128 v[184:187], v219 offset:37888
	ds_read_b128 v[220:223], v219 offset:38912
	ds_read_b128 v[224:227], v219 offset:39936
	global_load_lds_dwordx4 v188, s[12:13]
	s_mov_b32 m0, s46
	s_nop 0
	global_load_lds_dwordx4 v190, s[12:13]
	s_waitcnt vmcnt(8)
	s_waitcnt lgkmcnt(0)
	s_setprio 1
	s_barrier
	v_mfma_f32_16x16x32_bf16 v[114:117], v[66:69], v[162:165], v[114:117]
	v_mfma_f32_16x16x32_bf16 v[114:117], v[70:73], v[166:169], v[114:117]
	v_mfma_f32_16x16x32_bf16 v[110:113], v[66:69], v[170:173], v[110:113]
	v_mfma_f32_16x16x32_bf16 v[110:113], v[70:73], v[174:177], v[110:113]
	v_mfma_f32_16x16x32_bf16 v[78:81], v[66:69], v[178:181], v[78:81]
	v_mfma_f32_16x16x32_bf16 v[78:81], v[70:73], v[184:187], v[78:81]
	v_mfma_f32_16x16x32_bf16 v[74:77], v[66:69], v[220:223], v[74:77]
	v_mfma_f32_16x16x32_bf16 v[74:77], v[70:73], v[224:227], v[74:77]
	v_mfma_f32_16x16x32_bf16 v[106:109], v[82:85], v[162:165], v[106:109]
	v_mfma_f32_16x16x32_bf16 v[106:109], v[142:145], v[166:169], v[106:109]
	v_mfma_f32_16x16x32_bf16 v[102:105], v[82:85], v[170:173], v[102:105]
	v_mfma_f32_16x16x32_bf16 v[102:105], v[142:145], v[174:177], v[102:105]
	v_mfma_f32_16x16x32_bf16 v[138:141], v[82:85], v[178:181], v[138:141]
	v_mfma_f32_16x16x32_bf16 v[138:141], v[142:145], v[184:187], v[138:141]
	v_mfma_f32_16x16x32_bf16 v[134:137], v[82:85], v[220:223], v[134:137]
	v_mfma_f32_16x16x32_bf16 v[134:137], v[142:145], v[224:227], v[134:137]
	v_mfma_f32_16x16x32_bf16 v[98:101], v[146:149], v[162:165], v[98:101]
	v_mfma_f32_16x16x32_bf16 v[98:101], v[150:153], v[166:169], v[98:101]
	v_mfma_f32_16x16x32_bf16 v[94:97], v[146:149], v[170:173], v[94:97]
	v_mfma_f32_16x16x32_bf16 v[94:97], v[150:153], v[174:177], v[94:97]
	v_mfma_f32_16x16x32_bf16 v[130:133], v[146:149], v[178:181], v[130:133]
	v_mfma_f32_16x16x32_bf16 v[130:133], v[150:153], v[184:187], v[130:133]
	v_mfma_f32_16x16x32_bf16 v[126:129], v[146:149], v[220:223], v[126:129]
	v_mfma_f32_16x16x32_bf16 v[126:129], v[150:153], v[224:227], v[126:129]
	v_mfma_f32_16x16x32_bf16 v[90:93], v[154:157], v[162:165], v[90:93]
	v_mfma_f32_16x16x32_bf16 v[90:93], v[158:161], v[166:169], v[90:93]
	v_mfma_f32_16x16x32_bf16 v[86:89], v[154:157], v[170:173], v[86:89]
	v_mfma_f32_16x16x32_bf16 v[86:89], v[158:161], v[174:177], v[86:89]
	v_mfma_f32_16x16x32_bf16 v[122:125], v[154:157], v[178:181], v[122:125]
	v_mfma_f32_16x16x32_bf16 v[122:125], v[158:161], v[184:187], v[122:125]
	v_mfma_f32_16x16x32_bf16 v[118:121], v[154:157], v[220:223], v[118:121]
	v_mfma_f32_16x16x32_bf16 v[118:121], v[158:161], v[224:227], v[118:121]
	s_barrier
	s_setprio 0
	s_add_i32 s12, s19, s37
	s_mov_b32 m0, s12
	ds_read_b128 v[162:165], v219 offset:49152
	ds_read_b128 v[166:169], v219 offset:50176
	ds_read_b128 v[170:173], v219 offset:51200
	ds_read_b128 v[174:177], v219 offset:52224
	ds_read_b128 v[178:181], v219 offset:53248
	ds_read_b128 v[184:187], v219 offset:54272
	ds_read_b128 v[220:223], v219 offset:55296
	ds_read_b128 v[224:227], v219 offset:56320
	s_add_u32 s100, vcc_lo, 0x80
	s_addc_u32 s101, vcc_hi, 0
	global_load_lds_dwordx4 v182, s[100:101]
	s_add_i32 m0, s12, 0x2000
	s_add_u32 s12, vcc_lo, 0x80080
	s_addc_u32 s13, vcc_hi, 0
	s_add_i32 s19, s51, s37
	global_load_lds_dwordx4 v192, s[100:101]
	s_mov_b32 m0, s19
	s_nop 0
	global_load_lds_dwordx4 v182, s[12:13]
	s_add_i32 m0, s19, 0x2000
	s_nop 0
	global_load_lds_dwordx4 v192, s[12:13]
	s_mov_b32 m0, s45
	s_nop 0
	s_add_u32 s100, s40, 0x80
	s_addc_u32 s101, s41, 0
	global_load_lds_dwordx4 v188, s[100:101]
	s_mov_b32 m0, s24
	s_nop 0
	global_load_lds_dwordx4 v190, s[100:101]
	s_waitcnt vmcnt(8)
	s_waitcnt lgkmcnt(0)
	s_setprio 1
	s_barrier
	v_mfma_f32_16x16x32_bf16 v[30:33], v[66:69], v[162:165], v[30:33]
	v_mfma_f32_16x16x32_bf16 v[30:33], v[70:73], v[166:169], v[30:33]
	v_mfma_f32_16x16x32_bf16 v[26:29], v[66:69], v[170:173], v[26:29]
	v_mfma_f32_16x16x32_bf16 v[26:29], v[70:73], v[174:177], v[26:29]
	v_mfma_f32_16x16x32_bf16 v[62:65], v[66:69], v[178:181], v[62:65]
	v_mfma_f32_16x16x32_bf16 v[62:65], v[70:73], v[184:187], v[62:65]
	v_mfma_f32_16x16x32_bf16 v[58:61], v[66:69], v[220:223], v[58:61]
	v_mfma_f32_16x16x32_bf16 v[58:61], v[70:73], v[224:227], v[58:61]
	v_mfma_f32_16x16x32_bf16 v[22:25], v[82:85], v[162:165], v[22:25]
	v_mfma_f32_16x16x32_bf16 v[22:25], v[142:145], v[166:169], v[22:25]
	v_mfma_f32_16x16x32_bf16 v[18:21], v[82:85], v[170:173], v[18:21]
	v_mfma_f32_16x16x32_bf16 v[18:21], v[142:145], v[174:177], v[18:21]
	v_mfma_f32_16x16x32_bf16 v[54:57], v[82:85], v[178:181], v[54:57]
	v_mfma_f32_16x16x32_bf16 v[54:57], v[142:145], v[184:187], v[54:57]
	v_mfma_f32_16x16x32_bf16 v[50:53], v[82:85], v[220:223], v[50:53]
	v_mfma_f32_16x16x32_bf16 v[50:53], v[142:145], v[224:227], v[50:53]
	v_mfma_f32_16x16x32_bf16 v[14:17], v[146:149], v[162:165], v[14:17]
	v_mfma_f32_16x16x32_bf16 v[14:17], v[150:153], v[166:169], v[14:17]
	v_mfma_f32_16x16x32_bf16 v[10:13], v[146:149], v[170:173], v[10:13]
	v_mfma_f32_16x16x32_bf16 v[10:13], v[150:153], v[174:177], v[10:13]
	v_mfma_f32_16x16x32_bf16 v[46:49], v[146:149], v[178:181], v[46:49]
	v_mfma_f32_16x16x32_bf16 v[46:49], v[150:153], v[184:187], v[46:49]
	v_mfma_f32_16x16x32_bf16 v[38:41], v[146:149], v[220:223], v[38:41]
	v_mfma_f32_16x16x32_bf16 v[38:41], v[150:153], v[224:227], v[38:41]
	v_mfma_f32_16x16x32_bf16 v[6:9], v[154:157], v[162:165], v[6:9]
	v_mfma_f32_16x16x32_bf16 v[6:9], v[158:161], v[166:169], v[6:9]
	v_mfma_f32_16x16x32_bf16 v[2:5], v[154:157], v[170:173], v[2:5]
	v_mfma_f32_16x16x32_bf16 v[2:5], v[158:161], v[174:177], v[2:5]
	v_mfma_f32_16x16x32_bf16 v[34:37], v[154:157], v[178:181], v[34:37]
	v_mfma_f32_16x16x32_bf16 v[34:37], v[158:161], v[184:187], v[34:37]
	v_mfma_f32_16x16x32_bf16 v[42:45], v[154:157], v[220:223], v[42:45]
	v_mfma_f32_16x16x32_bf16 v[42:45], v[158:161], v[224:227], v[42:45]
	s_barrier
	s_setprio 0
	s_add_i32 s0, s0, 2
	s_add_u32 s66, s66, 0x100
	s_addc_u32 s67, s67, 0
	s_cmp_gt_u32 s0, 29
	s_mov_b64 s[12:13], s[96:97]
	s_cbranch_scc0 .LBB0_1327
	s_and_b64 vcc, exec, s[78:79]
	s_cbranch_vccz .LBB0_1330
	s_barrier

; #define PG8_STAGE(bufoff, gbase, voff) do { _Pragma("unroll") for (int _i = 0; _i < 2; ++_i) \
;         __builtin_amdgcn_global_load_lds((const unsigned*)((const char*)(gbase) + (voff)[_i]), (PG8_LAS unsigned*)(lds + (bufoff) + ldsw + _i * 8192), 16, 0, 0); } while (0)
; #define PG8_LDA(dst, b, h) do { _Pragma("unroll") for (int m = 0; m < 4; ++m) _Pragma("unroll") for (int k = 0; k < 2; ++k) dst[m][k] = *(const PG8_LAS bf16x8*)(lds + PG8_SA(b, h) + aoff + m * 2048 + k * 1024); } while (0)
; #define PG8_LDB(dst, b, h) do { _Pragma("unroll") for (int n = 0; n < 2; ++n) _Pragma("unroll") for (int k = 0; k < 2; ++k) dst[n][k] = *(const PG8_LAS bf16x8*)(lds + PG8_SB(b, h) + boff + n * 2048 + k * 1024); } while (0)
; #define PG8_WAIT_L(n) asm volatile("s_waitcnt lgkmcnt(" #n ")" ::: "memory")
; #define PG8_WAIT_V_SEL(sel) asm volatile("s_cmp_eq_u32 %0, 0\n\ts_cbranch_scc1 .Lw8_%=\n\ts_waitcnt vmcnt(22)\n\ts_branch .Lwd_%=\n.Lw8_%=:\n\ts_waitcnt vmcnt(8)\n.Lwd_%=:" :: "s"(sel) : "memory", "scc")
; #define PG8_BAR __builtin_amdgcn_s_barrier()
; #define PG8_SCHED __builtin_amdgcn_sched_barrier(0)
;     ...
;         for (int t = 0; t < nt * KREP; t += 2) {
;             const bool last = (t == nt * KREP - 2);
;             const int t1w = KREP > 1 ? ((t + 1) & (nt - 1)) : t + 1, t2w = KREP > 1 ? ((t + 2) & (nt - 1)) : t + 2;
;             const char* a1 = cA + (size_t)t1w * kstep;
;             const char* a2 = last ? nA : cA + (size_t)t2w * kstep; const char* b2 = last ? nB : cB + (size_t)t2w * kstep;
;             const char* a3 = a2 + kstep; const char* b3 = b2 + kstep;
;             if (last && has_next) S.a_ready(nxt);
;             const int relax = __builtin_amdgcn_readfirstlane((MK_RELAXW && t == 0 && ui > 0) ? 1 : 0);
;             if constexpr (SP2) {
;             PG8_LDB(B0, 0, 0); PG8_LDB(B1, 0, 1); PG8_SCHED; PG8_LDA(At, 0, 0); PG8_STAGE(PG8_SA(1, 1), a1 + hstep, voffA);
;             PG8_WAIT_V_SEL(relax);
;             PG8_WAIT_L(0); PG8_BAR; PG8_MMA(0, 0, At, B0); PG8_MMA(0, 1, At, B1); PG8_BAR; PG8_SCHED;
;             PG8_LDA(At, 0, 1); PG8_STAGE(PG8_SB(0, 0), b2, voffB); PG8_STAGE(PG8_SB(0, 1), b2 + hstep, voffB); PG8_STAGE(PG8_SA(0, 0), a2, voffA);
;             PG8_WAIT_V_SEL(relax);
;             PG8_WAIT_L(0); PG8_BAR; PG8_MMA(1, 0, At, B0); PG8_MMA(1, 1, At, B1); PG8_BAR; PG8_SCHED;
.LBB0_1648:
	s_add_u32 s10, s8, 0x100
	s_addc_u32 s11, s9, 0
	s_add_i32 s46, 0, 0x10000
	s_cmpk_eq_i32 s45, 0x52
	s_cselect_b32 s41, s1, s11
	s_cselect_b32 s40, s0, s10
	s_cselect_b32 s81, s79, s44
	s_cselect_b32 s80, s78, s37
	s_add_i32 s47, 0, 0x14000
	ds_read_b128 v[58:61], v206
	ds_read_b128 v[62:65], v206 offset:1024
	ds_read_b128 v[74:77], v206 offset:2048
	ds_read_b128 v[78:81], v206 offset:3072
	ds_read_b128 v[130:133], v206 offset:16384
	ds_read_b128 v[142:145], v206 offset:17408
	ds_read_b128 v[154:157], v206 offset:18432
	ds_read_b128 v[158:161], v206 offset:19456
	s_add_i32 m0, s91, 0xc000
	ds_read_b128 v[162:165], v246
	ds_read_b128 v[166:169], v246 offset:1024
	ds_read_b128 v[170:173], v246 offset:2048
	ds_read_b128 v[174:177], v246 offset:3072
	ds_read_b128 v[184:187], v246 offset:4096
	ds_read_b128 v[194:197], v246 offset:5120
	ds_read_b128 v[198:201], v246 offset:6144
	ds_read_b128 v[202:205], v246 offset:7168
	global_load_lds_dwordx4 v190, s[8:9]
	s_add_i32 m0, s91, 0xe000
	s_nop 0
	global_load_lds_dwordx4 v192, s[8:9]
	s_waitcnt vmcnt(8)
	s_waitcnt lgkmcnt(0)
	s_setprio 1
	s_barrier
	v_mfma_f32_16x16x32_bf16 v[150:153], v[58:61], v[162:165], v[150:153]
	v_mfma_f32_16x16x32_bf16 v[150:153], v[62:65], v[166:169], v[150:153]
	v_mfma_f32_16x16x32_bf16 v[126:129], v[58:61], v[170:173], v[126:129]
	v_mfma_f32_16x16x32_bf16 v[126:129], v[62:65], v[174:177], v[126:129]
	v_mfma_f32_16x16x32_bf16 v[110:113], v[58:61], v[184:187], v[110:113]
	v_mfma_f32_16x16x32_bf16 v[110:113], v[62:65], v[194:197], v[110:113]
	v_mfma_f32_16x16x32_bf16 v[94:97], v[58:61], v[198:201], v[94:97]
	v_mfma_f32_16x16x32_bf16 v[94:97], v[62:65], v[202:205], v[94:97]
	v_mfma_f32_16x16x32_bf16 v[146:149], v[74:77], v[162:165], v[146:149]
	v_mfma_f32_16x16x32_bf16 v[146:149], v[78:81], v[166:169], v[146:149]
	v_mfma_f32_16x16x32_bf16 v[122:125], v[74:77], v[170:173], v[122:125]
	v_mfma_f32_16x16x32_bf16 v[122:125], v[78:81], v[174:177], v[122:125]
	v_mfma_f32_16x16x32_bf16 v[106:109], v[74:77], v[184:187], v[106:109]
	v_mfma_f32_16x16x32_bf16 v[106:109], v[78:81], v[194:197], v[106:109]
	v_mfma_f32_16x16x32_bf16 v[90:93], v[74:77], v[198:201], v[90:93]
	v_mfma_f32_16x16x32_bf16 v[90:93], v[78:81], v[202:205], v[90:93]
	v_mfma_f32_16x16x32_bf16 v[138:141], v[130:133], v[162:165], v[138:141]
	v_mfma_f32_16x16x32_bf16 v[138:141], v[142:145], v[166:169], v[138:141]
	v_mfma_f32_16x16x32_bf16 v[118:121], v[130:133], v[170:173], v[118:121]
	v_mfma_f32_16x16x32_bf16 v[118:121], v[142:145], v[174:177], v[118:121]
	v_mfma_f32_16x16x32_bf16 v[102:105], v[130:133], v[184:187], v[102:105]
	v_mfma_f32_16x16x32_bf16 v[102:105], v[142:145], v[194:197], v[102:105]
	v_mfma_f32_16x16x32_bf16 v[86:89], v[130:133], v[198:201], v[86:89]
	v_mfma_f32_16x16x32_bf16 v[86:89], v[142:145], v[202:205], v[86:89]
	v_mfma_f32_16x16x32_bf16 v[134:137], v[154:157], v[162:165], v[134:137]
	v_mfma_f32_16x16x32_bf16 v[134:137], v[158:161], v[166:169], v[134:137]
	v_mfma_f32_16x16x32_bf16 v[114:117], v[154:157], v[170:173], v[114:117]
	v_mfma_f32_16x16x32_bf16 v[114:117], v[158:161], v[174:177], v[114:117]
	v_mfma_f32_16x16x32_bf16 v[98:101], v[154:157], v[184:187], v[98:101]
	v_mfma_f32_16x16x32_bf16 v[98:101], v[158:161], v[194:197], v[98:101]
	v_mfma_f32_16x16x32_bf16 v[82:85], v[154:157], v[198:201], v[82:85]
	v_mfma_f32_16x16x32_bf16 v[82:85], v[158:161], v[202:205], v[82:85]
	s_barrier
	s_setprio 0
	s_add_i32 s8, s46, s90
	s_mov_b32 m0, s8
	ds_read_b128 v[162:165], v246 offset:16384
	ds_read_b128 v[166:169], v246 offset:17408
	ds_read_b128 v[170:173], v246 offset:18432
	ds_read_b128 v[174:177], v246 offset:19456
	ds_read_b128 v[184:187], v246 offset:20480
	ds_read_b128 v[194:197], v246 offset:21504
	ds_read_b128 v[198:201], v246 offset:22528
	ds_read_b128 v[202:205], v246 offset:23552
	global_load_lds_dwordx4 v182, s[80:81]
	s_add_i32 m0, s8, 0x2000
	s_add_u32 s8, s80, 0x158000
	s_addc_u32 s9, s81, 0
	s_add_i32 s46, s47, s90
	global_load_lds_dwordx4 v188, s[80:81]
	s_mov_b32 m0, s46
	s_nop 0
	global_load_lds_dwordx4 v182, s[8:9]
	s_add_i32 m0, s46, 0x2000
	s_nop 0
	global_load_lds_dwordx4 v188, s[8:9]
	s_mov_b32 m0, s91
	s_nop 0
	global_load_lds_dwordx4 v178, s[40:41]
	s_mov_b32 m0, s92
	s_nop 0
	global_load_lds_dwordx4 v180, s[40:41]
	s_waitcnt vmcnt(8)
	s_waitcnt lgkmcnt(0)
	s_setprio 1
	s_barrier
	v_mfma_f32_16x16x32_bf16 v[70:73], v[58:61], v[162:165], v[70:73]
	v_mfma_f32_16x16x32_bf16 v[70:73], v[62:65], v[166:169], v[70:73]
	v_mfma_f32_16x16x32_bf16 v[46:49], v[58:61], v[170:173], v[46:49]
	v_mfma_f32_16x16x32_bf16 v[46:49], v[62:65], v[174:177], v[46:49]
	v_mfma_f32_16x16x32_bf16 v[30:33], v[58:61], v[184:187], v[30:33]
	v_mfma_f32_16x16x32_bf16 v[30:33], v[62:65], v[194:197], v[30:33]
	v_mfma_f32_16x16x32_bf16 v[14:17], v[58:61], v[198:201], v[14:17]
	v_mfma_f32_16x16x32_bf16 v[14:17], v[62:65], v[202:205], v[14:17]
	v_mfma_f32_16x16x32_bf16 v[66:69], v[74:77], v[162:165], v[66:69]
	v_mfma_f32_16x16x32_bf16 v[66:69], v[78:81], v[166:169], v[66:69]
	v_mfma_f32_16x16x32_bf16 v[42:45], v[74:77], v[170:173], v[42:45]
	v_mfma_f32_16x16x32_bf16 v[42:45], v[78:81], v[174:177], v[42:45]
	v_mfma_f32_16x16x32_bf16 v[26:29], v[74:77], v[184:187], v[26:29]
	v_mfma_f32_16x16x32_bf16 v[26:29], v[78:81], v[194:197], v[26:29]
	v_mfma_f32_16x16x32_bf16 v[10:13], v[74:77], v[198:201], v[10:13]
	v_mfma_f32_16x16x32_bf16 v[10:13], v[78:81], v[202:205], v[10:13]
	v_mfma_f32_16x16x32_bf16 v[54:57], v[130:133], v[162:165], v[54:57]
	v_mfma_f32_16x16x32_bf16 v[54:57], v[142:145], v[166:169], v[54:57]
	v_mfma_f32_16x16x32_bf16 v[38:41], v[130:133], v[170:173], v[38:41]
	v_mfma_f32_16x16x32_bf16 v[38:41], v[142:145], v[174:177], v[38:41]
	v_mfma_f32_16x16x32_bf16 v[22:25], v[130:133], v[184:187], v[22:25]
	v_mfma_f32_16x16x32_bf16 v[22:25], v[142:145], v[194:197], v[22:25]
	v_mfma_f32_16x16x32_bf16 v[6:9], v[130:133], v[198:201], v[6:9]
	v_mfma_f32_16x16x32_bf16 v[6:9], v[142:145], v[202:205], v[6:9]
	v_mfma_f32_16x16x32_bf16 v[50:53], v[154:157], v[162:165], v[50:53]
	v_mfma_f32_16x16x32_bf16 v[50:53], v[158:161], v[166:169], v[50:53]
	v_mfma_f32_16x16x32_bf16 v[34:37], v[154:157], v[170:173], v[34:37]
	v_mfma_f32_16x16x32_bf16 v[34:37], v[158:161], v[174:177], v[34:37]
	v_mfma_f32_16x16x32_bf16 v[18:21], v[154:157], v[184:187], v[18:21]
	v_mfma_f32_16x16x32_bf16 v[18:21], v[158:161], v[194:197], v[18:21]
	v_mfma_f32_16x16x32_bf16 v[2:5], v[154:157], v[198:201], v[2:5]
	v_mfma_f32_16x16x32_bf16 v[2:5], v[158:161], v[202:205], v[2:5]
	s_barrier
; #define PG8_STAGE(bufoff, gbase, voff) do { _Pragma("unroll") for (int _i = 0; _i < 2; ++_i) \
;         __builtin_amdgcn_global_load_lds((const unsigned*)((const char*)(gbase) + (voff)[_i]), (PG8_LAS unsigned*)(lds + (bufoff) + ldsw + _i * 8192), 16, 0, 0); } while (0)
; #define PG8_LDA(dst, b, h) do { _Pragma("unroll") for (int m = 0; m < 4; ++m) _Pragma("unroll") for (int k = 0; k < 2; ++k) dst[m][k] = *(const PG8_LAS bf16x8*)(lds + PG8_SA(b, h) + aoff + m * 2048 + k * 1024); } while (0)
; #define PG8_LDB(dst, b, h) do { _Pragma("unroll") for (int n = 0; n < 2; ++n) _Pragma("unroll") for (int k = 0; k < 2; ++k) dst[n][k] = *(const PG8_LAS bf16x8*)(lds + PG8_SB(b, h) + boff + n * 2048 + k * 1024); } while (0)
; #define PG8_WAIT_V(n) asm volatile("s_waitcnt vmcnt(" #n ")" ::: "memory")
; #define PG8_WAIT_L(n) asm volatile("s_waitcnt lgkmcnt(" #n ")" ::: "memory")
; #define PG8_WAIT_V_SEL(sel) asm volatile("s_cmp_eq_u32 %0, 0\n\ts_cbranch_scc1 .Lw8_%=\n\ts_waitcnt vmcnt(22)\n\ts_branch .Lwd_%=\n.Lw8_%=:\n\ts_waitcnt vmcnt(8)\n.Lwd_%=:" :: "s"(sel) : "memory", "scc")
; #define PG8_BAR __builtin_amdgcn_s_barrier()
; #define PG8_SCHED __builtin_amdgcn_sched_barrier(0)
;     ...
;             PG8_LDB(B0, 0, 0); PG8_LDB(B1, 0, 1); PG8_SCHED; PG8_LDA(At, 0, 0); PG8_STAGE(PG8_SA(1, 1), a1 + hstep, voffA);
;             PG8_WAIT_V_SEL(relax);
;             PG8_WAIT_L(0); PG8_BAR; PG8_MMA(0, 0, At, B0); PG8_MMA(0, 1, At, B1); PG8_BAR; PG8_SCHED;
;             PG8_LDA(At, 0, 1); PG8_STAGE(PG8_SB(0, 0), b2, voffB); PG8_STAGE(PG8_SB(0, 1), b2 + hstep, voffB); PG8_STAGE(PG8_SA(0, 0), a2, voffA);
;             PG8_WAIT_V_SEL(relax);
;             PG8_WAIT_L(0); PG8_BAR; PG8_MMA(1, 0, At, B0); PG8_MMA(1, 1, At, B1); PG8_BAR; PG8_SCHED;
;             PG8_LDB(B0, 1, 0); PG8_LDB(B1, 1, 1); PG8_SCHED; PG8_LDA(At, 1, 0); PG8_STAGE(PG8_SA(0, 1), a2 + hstep, voffA);
;             PG8_WAIT_V(8); PG8_WAIT_L(0); PG8_BAR; PG8_MMA(0, 0, At, B0); PG8_MMA(0, 1, At, B1); PG8_BAR; PG8_SCHED;
;             PG8_LDA(At, 1, 1); PG8_STAGE(PG8_SB(1, 0), b3, voffB); PG8_STAGE(PG8_SB(1, 1), b3 + hstep, voffB); PG8_STAGE(PG8_SA(1, 0), a3, voffA);
;             PG8_WAIT_V(8); PG8_WAIT_L(0); PG8_BAR; PG8_MMA(1, 0, At, B0); PG8_MMA(1, 1, At, B1); PG8_BAR; PG8_SCHED;
	s_setprio 0
	s_add_i32 s46, 0, 0x18000
	s_add_i32 s47, 0, 0x1c000
	ds_read_b128 v[58:61], v206 offset:32768
	ds_read_b128 v[62:65], v206 offset:33792
	ds_read_b128 v[74:77], v206 offset:34816
	ds_read_b128 v[78:81], v206 offset:35840
	ds_read_b128 v[130:133], v206 offset:49152
	ds_read_b128 v[142:145], v206 offset:50176
	ds_read_b128 v[154:157], v206 offset:51200
	ds_read_b128 v[158:161], v206 offset:52224
	s_add_u32 s8, s40, 0x158000
	s_addc_u32 s9, s41, 0
	s_mov_b32 m0, s93
	ds_read_b128 v[162:165], v246 offset:32768
	ds_read_b128 v[166:169], v246 offset:33792
	ds_read_b128 v[170:173], v246 offset:34816
	ds_read_b128 v[174:177], v246 offset:35840
	ds_read_b128 v[184:187], v246 offset:36864
	ds_read_b128 v[194:197], v246 offset:37888
	ds_read_b128 v[198:201], v246 offset:38912
	ds_read_b128 v[202:205], v246 offset:39936
	global_load_lds_dwordx4 v178, s[8:9]
	s_mov_b32 m0, s94
	s_nop 0
	global_load_lds_dwordx4 v180, s[8:9]
	s_waitcnt vmcnt(8)
	s_waitcnt lgkmcnt(0)
	s_setprio 1
	s_barrier
	v_mfma_f32_16x16x32_bf16 v[150:153], v[58:61], v[162:165], v[150:153]
	v_mfma_f32_16x16x32_bf16 v[150:153], v[62:65], v[166:169], v[150:153]
	v_mfma_f32_16x16x32_bf16 v[126:129], v[58:61], v[170:173], v[126:129]
	v_mfma_f32_16x16x32_bf16 v[126:129], v[62:65], v[174:177], v[126:129]
	v_mfma_f32_16x16x32_bf16 v[110:113], v[58:61], v[184:187], v[110:113]
	v_mfma_f32_16x16x32_bf16 v[110:113], v[62:65], v[194:197], v[110:113]
	v_mfma_f32_16x16x32_bf16 v[94:97], v[58:61], v[198:201], v[94:97]
	v_mfma_f32_16x16x32_bf16 v[94:97], v[62:65], v[202:205], v[94:97]
	v_mfma_f32_16x16x32_bf16 v[146:149], v[74:77], v[162:165], v[146:149]
	v_mfma_f32_16x16x32_bf16 v[146:149], v[78:81], v[166:169], v[146:149]
	v_mfma_f32_16x16x32_bf16 v[122:125], v[74:77], v[170:173], v[122:125]
	v_mfma_f32_16x16x32_bf16 v[122:125], v[78:81], v[174:177], v[122:125]
	v_mfma_f32_16x16x32_bf16 v[106:109], v[74:77], v[184:187], v[106:109]
	v_mfma_f32_16x16x32_bf16 v[106:109], v[78:81], v[194:197], v[106:109]
	v_mfma_f32_16x16x32_bf16 v[90:93], v[74:77], v[198:201], v[90:93]
	v_mfma_f32_16x16x32_bf16 v[90:93], v[78:81], v[202:205], v[90:93]
	v_mfma_f32_16x16x32_bf16 v[138:141], v[130:133], v[162:165], v[138:141]
	v_mfma_f32_16x16x32_bf16 v[138:141], v[142:145], v[166:169], v[138:141]
	v_mfma_f32_16x16x32_bf16 v[118:121], v[130:133], v[170:173], v[118:121]
	v_mfma_f32_16x16x32_bf16 v[118:121], v[142:145], v[174:177], v[118:121]
	v_mfma_f32_16x16x32_bf16 v[102:105], v[130:133], v[184:187], v[102:105]
	v_mfma_f32_16x16x32_bf16 v[102:105], v[142:145], v[194:197], v[102:105]
	v_mfma_f32_16x16x32_bf16 v[86:89], v[130:133], v[198:201], v[86:89]
	v_mfma_f32_16x16x32_bf16 v[86:89], v[142:145], v[202:205], v[86:89]
	v_mfma_f32_16x16x32_bf16 v[134:137], v[154:157], v[162:165], v[134:137]
	v_mfma_f32_16x16x32_bf16 v[134:137], v[158:161], v[166:169], v[134:137]
	v_mfma_f32_16x16x32_bf16 v[114:117], v[154:157], v[170:173], v[114:117]
	v_mfma_f32_16x16x32_bf16 v[114:117], v[158:161], v[174:177], v[114:117]
	v_mfma_f32_16x16x32_bf16 v[98:101], v[154:157], v[184:187], v[98:101]
	v_mfma_f32_16x16x32_bf16 v[98:101], v[158:161], v[194:197], v[98:101]
	v_mfma_f32_16x16x32_bf16 v[82:85], v[154:157], v[198:201], v[82:85]
	v_mfma_f32_16x16x32_bf16 v[82:85], v[158:161], v[202:205], v[82:85]
	s_barrier
	s_setprio 0
	s_add_i32 s8, s46, s90
	s_mov_b32 m0, s8
	ds_read_b128 v[162:165], v246 offset:49152
	ds_read_b128 v[166:169], v246 offset:50176
	ds_read_b128 v[170:173], v246 offset:51200
	ds_read_b128 v[174:177], v246 offset:52224
	ds_read_b128 v[184:187], v246 offset:53248
	ds_read_b128 v[194:197], v246 offset:54272
	ds_read_b128 v[198:201], v246 offset:55296
	ds_read_b128 v[202:205], v246 offset:56320
	s_add_u32 s100, s80, 0x80
	s_addc_u32 s101, s81, 0
	global_load_lds_dwordx4 v182, s[100:101]
	s_add_i32 m0, s8, 0x2000
	s_add_u32 s8, s80, 0x158080
	s_addc_u32 s9, s81, 0
	s_add_i32 vcc_lo, s47, s90
	global_load_lds_dwordx4 v188, s[100:101]
	s_mov_b32 m0, vcc_lo
	s_nop 0
	global_load_lds_dwordx4 v182, s[8:9]
	s_add_i32 m0, vcc_lo, 0x2000
	s_nop 0
	global_load_lds_dwordx4 v188, s[8:9]
	s_mov_b32 m0, s31
	s_nop 0
	s_add_u32 s100, s40, 0x80
	s_addc_u32 s101, s41, 0
	global_load_lds_dwordx4 v178, s[100:101]
	s_mov_b32 m0, s56
	s_nop 0
	global_load_lds_dwordx4 v180, s[100:101]
	s_waitcnt vmcnt(8)
	s_waitcnt lgkmcnt(0)
	s_setprio 1
	s_barrier
	v_mfma_f32_16x16x32_bf16 v[70:73], v[58:61], v[162:165], v[70:73]
	v_mfma_f32_16x16x32_bf16 v[70:73], v[62:65], v[166:169], v[70:73]
	v_mfma_f32_16x16x32_bf16 v[46:49], v[58:61], v[170:173], v[46:49]
	v_mfma_f32_16x16x32_bf16 v[46:49], v[62:65], v[174:177], v[46:49]
	v_mfma_f32_16x16x32_bf16 v[30:33], v[58:61], v[184:187], v[30:33]
	v_mfma_f32_16x16x32_bf16 v[30:33], v[62:65], v[194:197], v[30:33]
	v_mfma_f32_16x16x32_bf16 v[14:17], v[58:61], v[198:201], v[14:17]
	v_mfma_f32_16x16x32_bf16 v[14:17], v[62:65], v[202:205], v[14:17]
	v_mfma_f32_16x16x32_bf16 v[66:69], v[74:77], v[162:165], v[66:69]
	v_mfma_f32_16x16x32_bf16 v[66:69], v[78:81], v[166:169], v[66:69]
	v_mfma_f32_16x16x32_bf16 v[42:45], v[74:77], v[170:173], v[42:45]
	v_mfma_f32_16x16x32_bf16 v[42:45], v[78:81], v[174:177], v[42:45]
	v_mfma_f32_16x16x32_bf16 v[26:29], v[74:77], v[184:187], v[26:29]
	v_mfma_f32_16x16x32_bf16 v[26:29], v[78:81], v[194:197], v[26:29]
	v_mfma_f32_16x16x32_bf16 v[10:13], v[74:77], v[198:201], v[10:13]
	v_mfma_f32_16x16x32_bf16 v[10:13], v[78:81], v[202:205], v[10:13]
	v_mfma_f32_16x16x32_bf16 v[54:57], v[130:133], v[162:165], v[54:57]
	v_mfma_f32_16x16x32_bf16 v[54:57], v[142:145], v[166:169], v[54:57]
	v_mfma_f32_16x16x32_bf16 v[38:41], v[130:133], v[170:173], v[38:41]
	v_mfma_f32_16x16x32_bf16 v[38:41], v[142:145], v[174:177], v[38:41]
	v_mfma_f32_16x16x32_bf16 v[22:25], v[130:133], v[184:187], v[22:25]
	v_mfma_f32_16x16x32_bf16 v[22:25], v[142:145], v[194:197], v[22:25]
	v_mfma_f32_16x16x32_bf16 v[6:9], v[130:133], v[198:201], v[6:9]
	v_mfma_f32_16x16x32_bf16 v[6:9], v[142:145], v[202:205], v[6:9]
	v_mfma_f32_16x16x32_bf16 v[50:53], v[154:157], v[162:165], v[50:53]
	v_mfma_f32_16x16x32_bf16 v[50:53], v[158:161], v[166:169], v[50:53]
	v_mfma_f32_16x16x32_bf16 v[34:37], v[154:157], v[170:173], v[34:37]
	v_mfma_f32_16x16x32_bf16 v[34:37], v[158:161], v[174:177], v[34:37]
	v_mfma_f32_16x16x32_bf16 v[18:21], v[154:157], v[184:187], v[18:21]
	v_mfma_f32_16x16x32_bf16 v[18:21], v[158:161], v[194:197], v[18:21]
	v_mfma_f32_16x16x32_bf16 v[2:5], v[154:157], v[198:201], v[2:5]
	v_mfma_f32_16x16x32_bf16 v[2:5], v[158:161], v[202:205], v[2:5]
	s_barrier
	s_setprio 0
	s_add_i32 s45, s45, 2
	s_add_u32 s37, s37, 0x100
	s_addc_u32 s44, s44, 0
	s_cmpk_gt_u32 s45, 0x53
	s_mov_b64 s[8:9], s[10:11]
	s_cbranch_scc0 .LBB0_1648
	s_and_b64 vcc, exec, s[76:77]
	s_cbranch_vccz .LBB0_1651
	s_barrier
